# MoE weight f32->bf16 transposing conversion moved from the prep phase into the attention phase (half the blocks convert before, half after their attention item; hand-written tile code with 16-B stores
# speedup vs baseline: 1.2647x; 1.0133x over previous
; __device__ __forceinline__ u16 f2bf(float f) { return (u16)(pack2(f, 0.f) & 0xffffu); }
; __device__ __forceinline__ int tid_() { int t = threadIdx.x; asm volatile("" : "+v"(t)); return t; }
; __device__ __forceinline__ void convT_tile(const float* __restrict__ src, int lds, int k0, int c0, u16* __restrict__ dst, int Kd,
;                                            int rbase, int mode, int which, unsigned char* smem, const float* __restrict__ kscale = nullptr) {
;   float* tile = (float*)smem;
;   const int t = tid_();
;   float4 v4[4];
; #pragma unroll
;   for (int i = 0; i < 4; ++i) {
;     const f32x4 w_ = __builtin_nontemporal_load((const f32x4*)(src + (size_t)(k0 + i * 16 + (t >> 4)) * lds + c0 + (t & 15) * 4));
;     v4[i] = make_float4(w_[0], w_[1], w_[2], w_[3]);
;   }
; #pragma unroll
;   for (int i = 0; i < 4; ++i) {
;     const int kk = i * 16 + (t >> 4), cc = (t & 15) * 4;
;     const float sc = kscale ? kscale[k0 + kk] : 1.f;
;     tile[kk * 65 + cc + 0] = v4[i].x * sc; tile[kk * 65 + cc + 1] = v4[i].y * sc;
;     tile[kk * 65 + cc + 2] = v4[i].z * sc; tile[kk * 65 + cc + 3] = v4[i].w * sc;
;   }
;   __syncthreads();
; #pragma unroll
;   for (int i = 0; i < 16; ++i) {
;     const int cc = i * 4 + (t >> 6), kk = t & 63;
;     int row;
;     if (mode == 0) row = rbase + cc;
;     else { const int f = c0 + cc; row = (((f >> 4) * 2 + which) << 4) + (f & 15); }
;     dst[(size_t)row * Kd + k0 + kk] = f2bf(tile[kk * 65 + cc]);
;   }
;   __syncthreads();
; }
; __device__ __forceinline__ void conv_item(const Params& p, int it, unsigned char* smem) {
;     ...
;   r -= 4096;
;   {
;     const int e = r >> 7, r3 = r & 127, ct = r3 >> 3, kt = r3 & 7;
;     convT_tile(p.w_down + (size_t)(l * 16 + e) * 512 * 1024, 1024, kt * 64, ct * 64, p.WdT + (size_t)(l * 16 + e) * 1024 * 512, 512, ct * 64, 0, 0, smem);
;   }
.LBB0_26:
	s_mul_hi_i32 s0, s14, 0x9c09c09d
	s_add_i32 s0, s0, s14
	s_lshr_b32 s1, s0, 31
	s_ashr_i32 s0, s0, 12
	s_add_i32 s6, s0, s1
	s_mul_i32 s0, s6, 0xffffe5c0
	s_add_i32 s35, s14, s0
	s_cmpk_gt_i32 s35, 0xef
	s_mov_b64 s[0:1], -1
	s_cbranch_scc0 .LBB0_60
	s_cmpk_gt_u32 s35, 0x11f
	s_cbranch_scc0 .LBB0_49
	s_cmpk_gt_u32 s35, 0x13f
	s_cbranch_scc0 .LBB0_38
	s_cmpk_gt_u32 s35, 0x23f
	s_cbranch_scc0 .LBB0_35
	s_branch .LBB0_25
	s_nop 0
	v_mov_b64_e32 v[2:3], s[10:11]
	global_load_dwordx2 v[4:5], v[2:3], off offset:160
	s_add_i32 s0, s35, 0xffffedc0
	s_lshl_b32 s1, s6, 4
	s_lshl_b32 s4, s6, 9
	s_lshr_b32 s0, s0, 7
	v_mov_b32_e32 v6, v187
	s_sub_i32 s4, s23, s4
	s_add_i32 s0, s0, s1
	global_load_dwordx2 v[2:3], v[2:3], off offset:232
	s_and_b32 s12, s4, 0x3c0
	v_ashrrev_i32_e32 v9, 6, v6
	s_ashr_i32 s1, s0, 31
	s_and_b32 s7, s15, 0x1c0
	v_ashrrev_i32_e32 v8, 4, v6
	s_lshl_b32 s4, s12, 2
	v_add_u32_e32 v16, s12, v9
	s_lshl_b64 s[12:13], s[0:1], 21
	v_lshlrev_b32_e32 v7, 4, v6
	v_and_b32_e32 v24, 63, v6
	v_add_u32_e32 v6, s7, v8
	v_and_b32_e32 v18, 0xf0, v7
	v_ashrrev_i32_e32 v7, 31, v6
	v_lshlrev_b64 v[6:7], 12, v[6:7]
	v_lshlrev_b32_e32 v9, 2, v9
	v_mad_u64_u32 v[30:31], s[36:37], v8, s28, v[18:19]
	v_mad_u32_u24 v26, v24, s28, v9
	v_add_u32_e32 v29, 0x1040, v30
	v_add_u32_e32 v31, 0x1048, v30
	v_add_u32_e32 v62, 0x2080, v30
	v_add_u32_e32 v63, 0x2088, v30
	v_add_u32_e32 v64, 0x30c0, v30
	v_add_u32_e32 v65, 0x30c8, v30
	s_lshl_b64 s[0:1], s[0:1], 20
	v_add_u32_e32 v34, 8, v16
	v_add_u32_e32 v36, 12, v16
	v_add_u32_e32 v38, 16, v16
	v_add_u32_e32 v40, 20, v16
	v_add_u32_e32 v42, 24, v16
	v_add_u32_e32 v44, 28, v16
	v_add_u32_e32 v46, 32, v16
	v_add_u32_e32 v48, 36, v16
	v_add_u32_e32 v50, 40, v16
	v_add_u32_e32 v52, 44, v16
	v_add_u32_e32 v54, 48, v16
	v_add_u32_e32 v56, 52, v16
	v_add_u32_e32 v58, 56, v16
	v_add_u32_e32 v60, 60, v16
	v_ashrrev_i32_e32 v17, 31, v16
	v_ashrrev_i32_e32 v35, 31, v34
	v_ashrrev_i32_e32 v37, 31, v36
	v_ashrrev_i32_e32 v39, 31, v38
	v_ashrrev_i32_e32 v41, 31, v40
	v_ashrrev_i32_e32 v43, 31, v42
	v_ashrrev_i32_e32 v45, 31, v44
	v_ashrrev_i32_e32 v47, 31, v46
	v_ashrrev_i32_e32 v49, 31, v48
	v_ashrrev_i32_e32 v51, 31, v50
	v_ashrrev_i32_e32 v53, 31, v52
	v_ashrrev_i32_e32 v55, 31, v54
	v_ashrrev_i32_e32 v57, 31, v56
	v_ashrrev_i32_e32 v59, 31, v58
	v_ashrrev_i32_e32 v61, 31, v60
	v_lshlrev_b64 v[34:35], 10, v[34:35]
	v_lshlrev_b64 v[36:37], 10, v[36:37]
	v_lshlrev_b64 v[38:39], 10, v[38:39]
	v_lshlrev_b64 v[40:41], 10, v[40:41]
	v_lshlrev_b64 v[42:43], 10, v[42:43]
	v_lshlrev_b64 v[44:45], 10, v[44:45]
	v_lshlrev_b64 v[46:47], 10, v[46:47]
	v_lshlrev_b64 v[48:49], 10, v[48:49]
	v_lshlrev_b64 v[50:51], 10, v[50:51]
	v_lshlrev_b64 v[52:53], 10, v[52:53]
	v_lshlrev_b64 v[54:55], 10, v[54:55]
	v_lshlrev_b64 v[56:57], 10, v[56:57]
	v_lshlrev_b64 v[58:59], 10, v[58:59]
	v_lshlrev_b64 v[60:61], 10, v[60:61]
	s_waitcnt vmcnt(0) lgkmcnt(0)
	v_lshl_add_u64 v[4:5], v[4:5], 0, s[12:13]
	v_lshl_add_u64 v[4:5], v[4:5], 0, s[4:5]
	v_lshl_add_u64 v[4:5], v[4:5], 0, v[18:19]
	v_lshl_add_u64 v[20:21], v[4:5], 0, v[6:7]
	v_add_co_u32_e32 v22, vcc, s25, v20
	s_lshl_b32 s4, s7, 1
	s_nop 0
	v_addc_co_u32_e32 v23, vcc, 0, v21, vcc
	v_add_co_u32_e32 v32, vcc, s26, v20
	v_lshl_add_u64 v[2:3], v[2:3], 0, s[0:1]
	s_nop 0
	v_addc_co_u32_e32 v33, vcc, 0, v21, vcc
	global_load_dwordx4 v[4:7], v[20:21], off nt
	global_load_dwordx4 v[8:11], v[22:23], off nt
	global_load_dwordx4 v[12:15], v[32:33], off nt
	v_add_co_u32_e32 v20, vcc, s27, v20
	v_add_u32_e32 v32, 4, v16
	s_nop 0
	v_addc_co_u32_e32 v21, vcc, 0, v21, vcc
	global_load_dwordx4 v[20:23], v[20:21], off nt
	v_ashrrev_i32_e32 v33, 31, v32
	v_lshl_add_u64 v[2:3], v[2:3], 0, s[4:5]
	v_lshlrev_b32_e32 v18, 1, v24
	v_lshlrev_b64 v[16:17], 10, v[16:17]
	v_lshlrev_b64 v[32:33], 10, v[32:33]
	v_lshl_add_u64 v[2:3], v[2:3], 0, v[18:19]
	v_lshl_add_u64 v[16:17], v[2:3], 0, v[16:17]
	v_lshl_add_u64 v[32:33], v[2:3], 0, v[32:33]
	v_lshl_add_u64 v[34:35], v[2:3], 0, v[34:35]
	v_lshl_add_u64 v[36:37], v[2:3], 0, v[36:37]
	v_lshl_add_u64 v[38:39], v[2:3], 0, v[38:39]
	v_lshl_add_u64 v[40:41], v[2:3], 0, v[40:41]
	v_lshl_add_u64 v[42:43], v[2:3], 0, v[42:43]
	v_lshl_add_u64 v[44:45], v[2:3], 0, v[44:45]
	v_lshl_add_u64 v[46:47], v[2:3], 0, v[46:47]
	v_lshl_add_u64 v[48:49], v[2:3], 0, v[48:49]
	v_lshl_add_u64 v[50:51], v[2:3], 0, v[50:51]
	v_lshl_add_u64 v[52:53], v[2:3], 0, v[52:53]
	v_lshl_add_u64 v[54:55], v[2:3], 0, v[54:55]
	v_lshl_add_u64 v[56:57], v[2:3], 0, v[56:57]
	v_lshl_add_u64 v[58:59], v[2:3], 0, v[58:59]
	v_lshl_add_u64 v[2:3], v[2:3], 0, v[60:61]
	s_waitcnt vmcnt(0) lgkmcnt(0)
	ds_write2_b32 v30, v4, v5 offset1:1
	ds_write2_b32 v30, v6, v7 offset0:2 offset1:3
	ds_write2_b32 v29, v8, v9 offset1:1
	ds_write2_b32 v31, v10, v11 offset1:1
	ds_write2_b32 v62, v12, v13 offset1:1
	ds_write2_b32 v63, v14, v15 offset1:1
	ds_write2_b32 v64, v20, v21 offset1:1
	ds_write2_b32 v65, v22, v23 offset1:1
	s_waitcnt lgkmcnt(0)
	s_barrier
	ds_read2_b32 v[4:5], v26 offset1:4
	ds_read2_b32 v[6:7], v26 offset0:8 offset1:12
	ds_read2_b32 v[8:9], v26 offset0:16 offset1:20
	ds_read2_b32 v[10:11], v26 offset0:24 offset1:28
	ds_read2_b32 v[12:13], v26 offset0:32 offset1:36
	ds_read2_b32 v[14:15], v26 offset0:40 offset1:44
	ds_read2_b32 v[20:21], v26 offset0:48 offset1:52
	ds_read2_b32 v[22:23], v26 offset0:56 offset1:60
	s_waitcnt lgkmcnt(7)
	v_cvt_pk_bf16_f32 v4, v4, s0
	v_cvt_pk_bf16_f32 v5, v5, s0
	s_waitcnt lgkmcnt(6)
	v_cvt_pk_bf16_f32 v6, v6, s0
	s_waitcnt lgkmcnt(1)
	v_cvt_pk_bf16_f32 v18, v20, s0
	v_cvt_pk_bf16_f32 v20, v21, s0
	s_waitcnt lgkmcnt(0)
	v_cvt_pk_bf16_f32 v21, v22, s0
	v_cvt_pk_bf16_f32 v22, v23, s0
	v_cvt_pk_bf16_f32 v7, v7, s0
	v_cvt_pk_bf16_f32 v8, v8, s0
	v_cvt_pk_bf16_f32 v9, v9, s0
	v_cvt_pk_bf16_f32 v10, v10, s0
	v_cvt_pk_bf16_f32 v11, v11, s0
	v_cvt_pk_bf16_f32 v12, v12, s0
	v_cvt_pk_bf16_f32 v13, v13, s0
	v_cvt_pk_bf16_f32 v14, v14, s0
	v_cvt_pk_bf16_f32 v15, v15, s0
	global_store_short v[16:17], v4, off
	global_store_short v[32:33], v5, off
	global_store_short v[34:35], v6, off
	global_store_short v[36:37], v7, off
	global_store_short v[38:39], v8, off
	global_store_short v[40:41], v9, off
	global_store_short v[42:43], v10, off
	global_store_short v[44:45], v11, off
	global_store_short v[46:47], v12, off
	global_store_short v[48:49], v13, off
	global_store_short v[50:51], v14, off
	global_store_short v[52:53], v15, off
	global_store_short v[54:55], v18, off
	global_store_short v[56:57], v20, off
	global_store_short v[58:59], v21, off
	global_store_short v[2:3], v22, off
	s_waitcnt lgkmcnt(0)
	s_barrier
	s_mov_b64 s[0:1], 0

; __device__ __forceinline__ int tid_() { int t = threadIdx.x; asm volatile("" : "+v"(t)); return t; }
; __device__ __forceinline__ int bid_() { int b = blockIdx.x; asm volatile("" : "+s"(b)); return b; }
; __device__ __forceinline__ void phase_attn(const Params& p, int l, bool last, unsigned char* smem) {
;   float shift;
;   {
;     const int lane = tid_() & 63;
;     float mq = 0.f, mk = 0.f;
; #pragma unroll
;     for (int i = 0; i < 3; ++i) { mq = fmaxf(mq, fabsf(p.q_norm[l * 192 + lane + 64 * i])); mk = fmaxf(mk, fabsf(p.k_norm[l * 192 + lane + 64 * i])); }
; #pragma unroll
;     for (int o = 32; o; o >>= 1) { mq = fmaxf(mq, __shfl_xor(mq, o)); mk = fmaxf(mk, __shfl_xor(mk, o)); }
;     const float bound = 192.f * mq * mk * (0.07216878364870322f * 1.4426950408889634f);
;     shift = fmaxf(0.f, bound - 24.f);
;   }
;   const int x = bid_() & 7, j = bid_() >> 3, gb = gridDim.x >> 3;
;   for (int q = j; q < 64; q += gb) attn_item(p, x >> 2, x & 3, 2 + q, shift, smem);
;   if (!last)
;     for (int q = j; q < 2; q += gb) attn_item(p, x >> 2, x & 3, q, shift, smem);
.LBB0_763:
	s_or_b64 exec, exec, s[0:1]
	s_mov_b64 s[4:5], s[64:65]
	s_waitcnt lgkmcnt(0)
	s_barrier
	v_mov_b32_e32 v0, v187
	v_mov_b64_e32 v[2:3], s[4:5]
	global_load_dwordx4 v[2:5], v[2:3], off offset:112
	v_and_or_b32 v0, v0, 63, s94
	v_lshlrev_b64 v[6:7], 2, v[0:1]
	v_cmp_lt_i32_e32 vcc, v249, v227
	s_mov_b32 s18, s2
	s_mov_b32 s0, s2
	s_waitcnt vmcnt(0) lgkmcnt(0)
	v_lshl_add_u64 v[2:3], v[2:3], 0, v[6:7]
	global_load_dword v0, v[2:3], off
	v_lshl_add_u64 v[4:5], v[4:5], 0, v[6:7]
	global_load_dword v6, v[4:5], off
	global_load_dword v7, v[2:3], off offset:256
	global_load_dword v8, v[4:5], off offset:256
	s_nop 0
	global_load_dword v2, v[2:3], off offset:512
	v_cndmask_b32_e32 v3, v186, v249, vcc
	v_lshlrev_b32_e32 v229, 2, v3
	v_cmp_lt_i32_e32 vcc, v250, v227
	s_waitcnt vmcnt(0) lgkmcnt(0)
	v_max_f32_e64 v0, |v0|, |v0|
	v_max_f32_e32 v0, 0, v0
	v_max_f32_e64 v6, |v6|, |v6|
	v_max3_f32 v0, v0, |v7|, |v2|
	global_load_dword v2, v[4:5], off offset:512
	ds_bpermute_b32 v3, v229, v0
	v_max_f32_e32 v6, 0, v6
	s_and_b32 s19, s18, 7
	s_waitcnt lgkmcnt(0)
	v_max_f32_e32 v3, v3, v3
	v_max_f32_e32 v0, v0, v3
	s_ashr_i32 s8, s0, 3
	s_cmp_gt_i32 s8, 63
	s_mul_i32 s9, s19, 0x2100
	s_mul_i32 s40, s19, 0x318000
	s_mul_i32 s42, s19, 0x210000
	s_waitcnt vmcnt(0)
	v_max3_f32 v2, v6, |v8|, |v2|
	ds_bpermute_b32 v3, v229, v2
	s_waitcnt lgkmcnt(0)
	v_max_f32_e32 v3, v3, v3
	v_max_f32_e32 v2, v2, v3
	v_cndmask_b32_e32 v3, v186, v250, vcc
	v_lshlrev_b32_e32 v230, 2, v3
	ds_bpermute_b32 v3, v230, v0
	v_cmp_lt_i32_e32 vcc, v251, v227
	s_waitcnt lgkmcnt(0)
	v_max_f32_e32 v3, v3, v3
	v_max_f32_e32 v0, v0, v3
	ds_bpermute_b32 v3, v230, v2
	s_waitcnt lgkmcnt(0)
	v_max_f32_e32 v3, v3, v3
	v_max_f32_e32 v2, v2, v3
	v_cndmask_b32_e32 v3, v186, v251, vcc
	v_lshlrev_b32_e32 v231, 2, v3
	ds_bpermute_b32 v3, v231, v0
	v_cmp_lt_i32_e32 vcc, v252, v227
	s_waitcnt lgkmcnt(0)
	v_max_f32_e32 v3, v3, v3
	v_max_f32_e32 v0, v0, v3
	ds_bpermute_b32 v3, v231, v2
	s_waitcnt lgkmcnt(0)
	v_max_f32_e32 v3, v3, v3
	v_max_f32_e32 v2, v2, v3
	v_cndmask_b32_e32 v3, v186, v252, vcc
	v_lshlrev_b32_e32 v232, 2, v3
	ds_bpermute_b32 v3, v232, v0
	v_cmp_lt_i32_e32 vcc, v253, v227
	s_waitcnt lgkmcnt(0)
	v_max_f32_e32 v3, v3, v3
	v_max_f32_e32 v0, v0, v3
	ds_bpermute_b32 v3, v232, v2
	s_waitcnt lgkmcnt(0)
	v_max_f32_e32 v3, v3, v3
	v_max_f32_e32 v2, v2, v3
	v_cndmask_b32_e32 v3, v186, v253, vcc
	v_lshlrev_b32_e32 v233, 2, v3
	ds_bpermute_b32 v3, v233, v0
	v_cmp_lt_i32_e32 vcc, v212, v227
	s_waitcnt lgkmcnt(0)
	v_max_f32_e32 v3, v3, v3
	v_max_f32_e32 v0, v0, v3
	ds_bpermute_b32 v3, v233, v2
	s_waitcnt lgkmcnt(0)
	v_max_f32_e32 v3, v3, v3
	v_max_f32_e32 v2, v2, v3
	v_cndmask_b32_e32 v3, v186, v212, vcc
	v_lshlrev_b32_e32 v234, 2, v3
	ds_bpermute_b32 v3, v234, v0
	s_waitcnt lgkmcnt(0)
	v_max_f32_e32 v3, v3, v3
	v_max_f32_e32 v0, v0, v3
	ds_bpermute_b32 v3, v234, v2
	v_mul_f32_e32 v0, 0x43400000, v0
	s_waitcnt lgkmcnt(0)
	v_max_f32_e32 v3, v3, v3
	v_max_f32_e32 v2, v2, v3
	v_mul_f32_e32 v0, v2, v0
	v_mov_b32_e32 v2, 0xc1c00000
	v_fmamk_f32 v0, v0, 0x3dd53b94, v2
	v_max_f32_e32 v2, 0, v0
	v_cmp_lt_f32_e64 s[38:39], 0, v2
	s_cbranch_scc1 .LBB0_776
	s_bitcmp1_b32 s2, 8
	s_cbranch_scc0 .Lcv_ret_pre
	s_mov_b32 s32, 0
	s_branch .Lcv_entry
.Lcv_ret_pre:
	s_lshr_b32 s0, s19, 2
	s_lshl_b32 s1, s18, 7
	s_and_b32 s1, s1, 0x180
	s_lshl_b32 s48, s0, 13
	s_lshl_b32 s49, s0, 8
	s_mov_b32 s41, s95
	s_mov_b32 s43, s95
	s_addk_i32 s48, 0xff00
	s_bitset1_b32 s49, 14
	v_mov_b32_e32 v3, v2
	v_mov_b32_e32 v4, v2
	v_mov_b32_e32 v5, v2
	s_lshl_b32 s46, s1, 1
	s_mov_b32 s50, s8
	s_branch .LBB0_766

; __device__ __forceinline__ u16 f2bf(float f) { return (u16)(pack2(f, 0.f) & 0xffffu); }
; __device__ __forceinline__ int tid_() { int t = threadIdx.x; asm volatile("" : "+v"(t)); return t; }
; __device__ __forceinline__ void convT_tile(const float* __restrict__ src, int lds, int k0, int c0, u16* __restrict__ dst, int Kd,
;                                            int rbase, int mode, int which, unsigned char* smem, const float* __restrict__ kscale = nullptr) {
;   float* tile = (float*)smem;
;   const int t = tid_();
;   float4 v4[4];
; #pragma unroll
;   for (int i = 0; i < 4; ++i) {
;     const f32x4 w_ = __builtin_nontemporal_load((const f32x4*)(src + (size_t)(k0 + i * 16 + (t >> 4)) * lds + c0 + (t & 15) * 4));
;     v4[i] = make_float4(w_[0], w_[1], w_[2], w_[3]);
;   }
; #pragma unroll
;   for (int i = 0; i < 4; ++i) {
;     const int kk = i * 16 + (t >> 4), cc = (t & 15) * 4;
;     const float sc = kscale ? kscale[k0 + kk] : 1.f;
;     tile[kk * 65 + cc + 0] = v4[i].x * sc; tile[kk * 65 + cc + 1] = v4[i].y * sc;
;     tile[kk * 65 + cc + 2] = v4[i].z * sc; tile[kk * 65 + cc + 3] = v4[i].w * sc;
;   }
;   __syncthreads();
; #pragma unroll
;   for (int i = 0; i < 16; ++i) {
;     const int cc = i * 4 + (t >> 6), kk = t & 63;
;     int row;
;     if (mode == 0) row = rbase + cc;
;     else { const int f = c0 + cc; row = (((f >> 4) * 2 + which) << 4) + (f & 15); }
;     dst[(size_t)row * Kd + k0 + kk] = f2bf(tile[kk * 65 + cc]);
;   }
;   __syncthreads();
; }
; __device__ __forceinline__ void conv_item(const Params& p, int it, unsigned char* smem) {
;     ...
;   if (r < 4096) {
;     const int which = r >> 11, r2 = r & 2047, e = r2 >> 7, r3 = r2 & 127, ct = r3 >> 4, kt = r3 & 15;
;     const float* src = (which ? p.w_up : p.w_gate) + (size_t)(l * 16 + e) * 1024 * 512;
;     convT_tile(src, 512, kt * 64, ct * 64, p.WguT + (size_t)(l * 16 + e) * 1024 * 1024, 1024, 0, 1, which, smem);
;     return;
;   }
;   r -= 4096;
;   {
;     const int e = r >> 7, r3 = r & 127, ct = r3 >> 3, kt = r3 & 7;
;     convT_tile(p.w_down + (size_t)(l * 16 + e) * 512 * 1024, 1024, kt * 64, ct * 64, p.WdT + (size_t)(l * 16 + e) * 1024 * 512, 512, ct * 64, 0, 0, smem);
;   }
.Lcv_entry:
	s_load_dwordx2 s[52:53], s[4:5], 0x90
	s_load_dwordx2 s[54:55], s[4:5], 0x98
	s_load_dwordx2 s[56:57], s[4:5], 0xa0
	s_load_dwordx2 s[98:99], s[4:5], 0xe0
	s_load_dwordx2 s[100:101], s[4:5], 0xe8
	v_lshrrev_b32_e32 v98, 4, v187
	v_add_u32_e32 v99, 16, v98
	v_add_u32_e32 v100, 32, v98
	v_add_u32_e32 v101, 48, v98
	v_and_b32_e32 v122, 15, v187
	v_lshlrev_b32_e32 v102, 4, v122
	v_lshrrev_b32_e32 v123, 3, v187
	v_and_b32_e32 v122, 7, v187
	v_lshrrev_b32_e32 v36, 4, v123
	v_and_b32_e32 v37, 15, v123
	v_lshl_add_u32 v36, v36, 5, v37
	v_lshlrev_b32_e32 v36, 11, v36
	v_lshl_add_u32 v103, v122, 4, v36
	v_lshlrev_b32_e32 v36, 10, v123
	v_lshl_add_u32 v105, v122, 4, v36
	v_add_u32_e32 v123, 32, v123
	v_lshrrev_b32_e32 v36, 4, v123
	v_and_b32_e32 v37, 15, v123
	v_lshl_add_u32 v36, v36, 5, v37
	v_lshlrev_b32_e32 v36, 11, v36
	v_lshl_add_u32 v104, v122, 4, v36
	v_lshlrev_b32_e32 v36, 10, v123
	v_lshl_add_u32 v106, v122, 4, v36
	v_subrev_u32_e32 v123, 32, v123
	v_mul_u32_u24_e32 v36, 0x820, v122
	v_lshl_add_u32 v115, v123, 2, v36
	v_mul_u32_u24_e32 v37, 0x104, v98
	v_add_u32_e32 v107, v37, v102
	v_add_u32_e32 v111, 0x4100, v107
	v_mul_u32_u24_e32 v37, 0x104, v99
	v_add_u32_e32 v108, v37, v102
	v_add_u32_e32 v112, 0x4100, v108
	v_mul_u32_u24_e32 v37, 0x104, v100
	v_add_u32_e32 v109, v37, v102
	v_add_u32_e32 v113, 0x4100, v109
	v_mul_u32_u24_e32 v37, 0x104, v101
	v_add_u32_e32 v110, v37, v102
	v_add_u32_e32 v114, 0x4100, v110
	s_waitcnt lgkmcnt(0)
	s_barrier
	s_add_i32 s59, s2, 0x0
	s_cmp_lt_u32 s59, 0x1000
	s_cbranch_scc0 .Lcv_sd0
	s_lshr_b32 s60, s59, 11
	s_bfe_u32 s71, s59, 0x40007
	s_bfe_u32 s35, s59, 0x30004
	s_and_b32 s51, s59, 15
	s_lshl_b32 s0, s36, 4
	s_add_i32 s71, s71, s0
	s_lshl_b32 s71, s71, 21
	s_lshl_b32 s0, s51, 17
	s_add_i32 s71, s71, s0
	s_lshl_b32 s0, s35, 8
	s_add_i32 s71, s71, s0
	s_cmp_eq_u32 s60, 0
	s_cselect_b32 s88, s52, s54
	s_cselect_b32 s89, s53, s55
	s_add_u32 s88, s88, s71
	s_addc_u32 s89, s89, 0
	s_mov_b32 s94, 11
	s_branch .Lcv_se0
.Lcv_sd0:
	s_sub_i32 s59, s59, 0x1000
	s_lshr_b32 s71, s59, 7
	s_bfe_u32 s35, s59, 0x40003
	s_and_b32 s51, s59, 7
	s_lshl_b32 s0, s36, 4
	s_add_i32 s71, s71, s0
	s_lshl_b32 s71, s71, 21
	s_lshl_b32 s0, s51, 18
	s_add_i32 s71, s71, s0
	s_lshl_b32 s0, s35, 8
	s_add_i32 s71, s71, s0
	s_add_u32 s88, s56, s71
	s_addc_u32 s89, s57, 0
	s_mov_b32 s94, 12
.Lcv_se0:
	v_lshl_add_u32 v116, v98, s94, v102
	v_lshl_add_u32 v117, v99, s94, v102
	v_lshl_add_u32 v118, v100, s94, v102
	v_lshl_add_u32 v119, v101, s94, v102
	global_load_dwordx4 v[132:135], v116, s[88:89] nt
	global_load_dwordx4 v[136:139], v117, s[88:89] nt
	global_load_dwordx4 v[140:143], v118, s[88:89] nt
	global_load_dwordx4 v[144:147], v119, s[88:89] nt
	s_add_i32 s59, s2, 0x200
	s_cmp_lt_u32 s59, 0x1000
	s_cbranch_scc0 .Lcv_sd1
	s_lshr_b32 s60, s59, 11
	s_bfe_u32 s71, s59, 0x40007
	s_bfe_u32 s35, s59, 0x30004
	s_and_b32 s51, s59, 15
	s_lshl_b32 s0, s36, 4
	s_add_i32 s71, s71, s0
	s_lshl_b32 s71, s71, 21
	s_lshl_b32 s0, s51, 17
	s_add_i32 s71, s71, s0
	s_lshl_b32 s0, s35, 8
	s_add_i32 s71, s71, s0
	s_cmp_eq_u32 s60, 0
	s_cselect_b32 s88, s52, s54
	s_cselect_b32 s89, s53, s55
	s_add_u32 s88, s88, s71
	s_addc_u32 s89, s89, 0
	s_mov_b32 s94, 11
	s_branch .Lcv_se1

; __device__ __forceinline__ u16 f2bf(float f) { return (u16)(pack2(f, 0.f) & 0xffffu); }
; __device__ __forceinline__ int tid_() { int t = threadIdx.x; asm volatile("" : "+v"(t)); return t; }
; __device__ __forceinline__ void convT_tile(const float* __restrict__ src, int lds, int k0, int c0, u16* __restrict__ dst, int Kd,
;                                            int rbase, int mode, int which, unsigned char* smem, const float* __restrict__ kscale = nullptr) {
;   float* tile = (float*)smem;
;   const int t = tid_();
;   float4 v4[4];
; #pragma unroll
;   for (int i = 0; i < 4; ++i) {
;     const f32x4 w_ = __builtin_nontemporal_load((const f32x4*)(src + (size_t)(k0 + i * 16 + (t >> 4)) * lds + c0 + (t & 15) * 4));
;     v4[i] = make_float4(w_[0], w_[1], w_[2], w_[3]);
;   }
; #pragma unroll
;   for (int i = 0; i < 4; ++i) {
;     const int kk = i * 16 + (t >> 4), cc = (t & 15) * 4;
;     const float sc = kscale ? kscale[k0 + kk] : 1.f;
;     tile[kk * 65 + cc + 0] = v4[i].x * sc; tile[kk * 65 + cc + 1] = v4[i].y * sc;
;     tile[kk * 65 + cc + 2] = v4[i].z * sc; tile[kk * 65 + cc + 3] = v4[i].w * sc;
;   }
;   __syncthreads();
; #pragma unroll
;   for (int i = 0; i < 16; ++i) {
;     const int cc = i * 4 + (t >> 6), kk = t & 63;
;     int row;
;     if (mode == 0) row = rbase + cc;
;     else { const int f = c0 + cc; row = (((f >> 4) * 2 + which) << 4) + (f & 15); }
;     dst[(size_t)row * Kd + k0 + kk] = f2bf(tile[kk * 65 + cc]);
;   }
;   __syncthreads();
; }
.Lcv_se1:
	v_lshl_add_u32 v116, v98, s94, v102
	v_lshl_add_u32 v117, v99, s94, v102
	v_lshl_add_u32 v118, v100, s94, v102
	v_lshl_add_u32 v119, v101, s94, v102
	global_load_dwordx4 v[148:151], v116, s[88:89] nt
	global_load_dwordx4 v[152:155], v117, s[88:89] nt
	global_load_dwordx4 v[156:159], v118, s[88:89] nt
	global_load_dwordx4 v[160:163], v119, s[88:89] nt
	s_add_i32 s59, s2, 0x0
	s_cmp_lt_u32 s59, 0x1000
	s_cbranch_scc0 .Lcv_dd0
	s_lshr_b32 s60, s59, 11
	s_bfe_u32 s71, s59, 0x40007
	s_bfe_u32 s35, s59, 0x30004
	s_and_b32 s51, s59, 15
	s_lshl_b32 s0, s36, 4
	s_add_i32 s71, s71, s0
	s_lshl_b32 s71, s71, 21
	s_lshl_b32 s35, s35, 7
	s_lshl_b32 s60, s60, 4
	s_add_i32 s35, s35, s60
	s_lshl_b32 s35, s35, 11
	s_add_i32 s71, s71, s35
	s_lshl_b32 s51, s51, 7
	s_add_i32 s71, s71, s51
	s_add_u32 s0, s98, s71
	s_addc_u32 s1, s99, 0
	v_mov_b32_e32 v120, v103
	v_mov_b32_e32 v121, v104
	s_branch .Lcv_de0
.Lcv_dd0:
	s_sub_i32 s59, s59, 0x1000
	s_lshr_b32 s71, s59, 7
	s_bfe_u32 s35, s59, 0x40003
	s_and_b32 s51, s59, 7
	s_lshl_b32 s0, s36, 4
	s_add_i32 s71, s71, s0
	s_lshl_b32 s71, s71, 20
	s_lshl_b32 s35, s35, 16
	s_add_i32 s71, s71, s35
	s_lshl_b32 s51, s51, 7
	s_add_i32 s71, s71, s51
	s_add_u32 s0, s100, s71
	s_addc_u32 s1, s101, 0
	v_mov_b32_e32 v120, v105
	v_mov_b32_e32 v121, v106
.Lcv_de0:
	s_waitcnt vmcnt(4)
	ds_write2_b32 v107, v132, v133 offset1:1
	ds_write2_b32 v107, v134, v135 offset0:2 offset1:3
	ds_write2_b32 v108, v136, v137 offset1:1
	ds_write2_b32 v108, v138, v139 offset0:2 offset1:3
	ds_write2_b32 v109, v140, v141 offset1:1
	ds_write2_b32 v109, v142, v143 offset0:2 offset1:3
	ds_write2_b32 v110, v144, v145 offset1:1
	ds_write2_b32 v110, v146, v147 offset0:2 offset1:3
	s_waitcnt lgkmcnt(0)
	s_barrier
	ds_read_b32 v72, v115 offset:0
	ds_read_b32 v73, v115 offset:260
	ds_read_b32 v74, v115 offset:520
	ds_read_b32 v75, v115 offset:780
	ds_read_b32 v76, v115 offset:1040
	ds_read_b32 v77, v115 offset:1300
	ds_read_b32 v78, v115 offset:1560
	ds_read_b32 v79, v115 offset:1820
	ds_read_b32 v26, v115 offset:128
	ds_read_b32 v27, v115 offset:388
	ds_read_b32 v28, v115 offset:648
	ds_read_b32 v29, v115 offset:908
	ds_read_b32 v30, v115 offset:1168
	ds_read_b32 v31, v115 offset:1428
	ds_read_b32 v32, v115 offset:1688
	ds_read_b32 v33, v115 offset:1948
	s_waitcnt lgkmcnt(8)
	v_cvt_pk_bf16_f32 v124, v72, v73
	v_cvt_pk_bf16_f32 v125, v74, v75
	v_cvt_pk_bf16_f32 v126, v76, v77
	v_cvt_pk_bf16_f32 v127, v78, v79
	global_store_dwordx4 v120, v[124:127], s[0:1]
	s_waitcnt lgkmcnt(0)
	v_cvt_pk_bf16_f32 v128, v26, v27
	v_cvt_pk_bf16_f32 v129, v28, v29
	v_cvt_pk_bf16_f32 v130, v30, v31
	v_cvt_pk_bf16_f32 v131, v32, v33
	global_store_dwordx4 v121, v[128:131], s[0:1]
	s_add_i32 s59, s2, 0x400
	s_cmp_lt_u32 s59, 0x1000
	s_cbranch_scc0 .Lcv_sd2
	s_lshr_b32 s60, s59, 11
	s_bfe_u32 s71, s59, 0x40007
	s_bfe_u32 s35, s59, 0x30004
	s_and_b32 s51, s59, 15
	s_lshl_b32 s0, s36, 4
	s_add_i32 s71, s71, s0
	s_lshl_b32 s71, s71, 21
	s_lshl_b32 s0, s51, 17
	s_add_i32 s71, s71, s0
	s_lshl_b32 s0, s35, 8
	s_add_i32 s71, s71, s0
	s_cmp_eq_u32 s60, 0
	s_cselect_b32 s88, s52, s54
	s_cselect_b32 s89, s53, s55
	s_add_u32 s88, s88, s71
	s_addc_u32 s89, s89, 0
	s_mov_b32 s94, 11
	s_branch .Lcv_se2

; __device__ __forceinline__ u16 f2bf(float f) { return (u16)(pack2(f, 0.f) & 0xffffu); }
; __device__ __forceinline__ int tid_() { int t = threadIdx.x; asm volatile("" : "+v"(t)); return t; }
; __device__ __forceinline__ void convT_tile(const float* __restrict__ src, int lds, int k0, int c0, u16* __restrict__ dst, int Kd,
;                                            int rbase, int mode, int which, unsigned char* smem, const float* __restrict__ kscale = nullptr) {
;   float* tile = (float*)smem;
;   const int t = tid_();
;   float4 v4[4];
; #pragma unroll
;   for (int i = 0; i < 4; ++i) {
;     const f32x4 w_ = __builtin_nontemporal_load((const f32x4*)(src + (size_t)(k0 + i * 16 + (t >> 4)) * lds + c0 + (t & 15) * 4));
;     v4[i] = make_float4(w_[0], w_[1], w_[2], w_[3]);
;   }
; #pragma unroll
;   for (int i = 0; i < 4; ++i) {
;     const int kk = i * 16 + (t >> 4), cc = (t & 15) * 4;
;     const float sc = kscale ? kscale[k0 + kk] : 1.f;
;     tile[kk * 65 + cc + 0] = v4[i].x * sc; tile[kk * 65 + cc + 1] = v4[i].y * sc;
;     tile[kk * 65 + cc + 2] = v4[i].z * sc; tile[kk * 65 + cc + 3] = v4[i].w * sc;
;   }
;   __syncthreads();
; #pragma unroll
;   for (int i = 0; i < 16; ++i) {
;     const int cc = i * 4 + (t >> 6), kk = t & 63;
;     int row;
;     if (mode == 0) row = rbase + cc;
;     else { const int f = c0 + cc; row = (((f >> 4) * 2 + which) << 4) + (f & 15); }
;     dst[(size_t)row * Kd + k0 + kk] = f2bf(tile[kk * 65 + cc]);
;   }
;   __syncthreads();
; }
; __device__ __forceinline__ void conv_item(const Params& p, int it, unsigned char* smem) {
;     ...
;   if (r < 4096) {
;     const int which = r >> 11, r2 = r & 2047, e = r2 >> 7, r3 = r2 & 127, ct = r3 >> 4, kt = r3 & 15;
;     const float* src = (which ? p.w_up : p.w_gate) + (size_t)(l * 16 + e) * 1024 * 512;
;     convT_tile(src, 512, kt * 64, ct * 64, p.WguT + (size_t)(l * 16 + e) * 1024 * 1024, 1024, 0, 1, which, smem);
;     return;
;   }
;   r -= 4096;
;   {
;     const int e = r >> 7, r3 = r & 127, ct = r3 >> 3, kt = r3 & 7;
;     convT_tile(p.w_down + (size_t)(l * 16 + e) * 512 * 1024, 1024, kt * 64, ct * 64, p.WdT + (size_t)(l * 16 + e) * 1024 * 512, 512, ct * 64, 0, 0, smem);
;   }
.Lcv_se2:
	v_lshl_add_u32 v116, v98, s94, v102
	v_lshl_add_u32 v117, v99, s94, v102
	v_lshl_add_u32 v118, v100, s94, v102
	v_lshl_add_u32 v119, v101, s94, v102
	global_load_dwordx4 v[132:135], v116, s[88:89] nt
	global_load_dwordx4 v[136:139], v117, s[88:89] nt
	global_load_dwordx4 v[140:143], v118, s[88:89] nt
	global_load_dwordx4 v[144:147], v119, s[88:89] nt
	s_add_i32 s59, s2, 0x200
	s_cmp_lt_u32 s59, 0x1000
	s_cbranch_scc0 .Lcv_dd1
	s_lshr_b32 s60, s59, 11
	s_bfe_u32 s71, s59, 0x40007
	s_bfe_u32 s35, s59, 0x30004
	s_and_b32 s51, s59, 15
	s_lshl_b32 s0, s36, 4
	s_add_i32 s71, s71, s0
	s_lshl_b32 s71, s71, 21
	s_lshl_b32 s35, s35, 7
	s_lshl_b32 s60, s60, 4
	s_add_i32 s35, s35, s60
	s_lshl_b32 s35, s35, 11
	s_add_i32 s71, s71, s35
	s_lshl_b32 s51, s51, 7
	s_add_i32 s71, s71, s51
	s_add_u32 s0, s98, s71
	s_addc_u32 s1, s99, 0
	v_mov_b32_e32 v120, v103
	v_mov_b32_e32 v121, v104
	s_branch .Lcv_de1

; __device__ __forceinline__ u16 f2bf(float f) { return (u16)(pack2(f, 0.f) & 0xffffu); }
; __device__ __forceinline__ int tid_() { int t = threadIdx.x; asm volatile("" : "+v"(t)); return t; }
; __device__ __forceinline__ void convT_tile(const float* __restrict__ src, int lds, int k0, int c0, u16* __restrict__ dst, int Kd,
;                                            int rbase, int mode, int which, unsigned char* smem, const float* __restrict__ kscale = nullptr) {
;   float* tile = (float*)smem;
;   const int t = tid_();
;   float4 v4[4];
; #pragma unroll
;   for (int i = 0; i < 4; ++i) {
;     const f32x4 w_ = __builtin_nontemporal_load((const f32x4*)(src + (size_t)(k0 + i * 16 + (t >> 4)) * lds + c0 + (t & 15) * 4));
;     v4[i] = make_float4(w_[0], w_[1], w_[2], w_[3]);
;   }
; #pragma unroll
;   for (int i = 0; i < 4; ++i) {
;     const int kk = i * 16 + (t >> 4), cc = (t & 15) * 4;
;     const float sc = kscale ? kscale[k0 + kk] : 1.f;
;     tile[kk * 65 + cc + 0] = v4[i].x * sc; tile[kk * 65 + cc + 1] = v4[i].y * sc;
;     tile[kk * 65 + cc + 2] = v4[i].z * sc; tile[kk * 65 + cc + 3] = v4[i].w * sc;
;   }
;   __syncthreads();
; #pragma unroll
;   for (int i = 0; i < 16; ++i) {
;     const int cc = i * 4 + (t >> 6), kk = t & 63;
;     int row;
;     if (mode == 0) row = rbase + cc;
;     else { const int f = c0 + cc; row = (((f >> 4) * 2 + which) << 4) + (f & 15); }
;     dst[(size_t)row * Kd + k0 + kk] = f2bf(tile[kk * 65 + cc]);
;   }
;   __syncthreads();
; }
.Lcv_de1:
	s_waitcnt vmcnt(6)
	ds_write2_b32 v111, v148, v149 offset1:1
	ds_write2_b32 v111, v150, v151 offset0:2 offset1:3
	ds_write2_b32 v112, v152, v153 offset1:1
	ds_write2_b32 v112, v154, v155 offset0:2 offset1:3
	ds_write2_b32 v113, v156, v157 offset1:1
	ds_write2_b32 v113, v158, v159 offset0:2 offset1:3
	ds_write2_b32 v114, v160, v161 offset1:1
	ds_write2_b32 v114, v162, v163 offset0:2 offset1:3
	s_waitcnt lgkmcnt(0)
	s_barrier
	ds_read_b32 v72, v115 offset:16640
	ds_read_b32 v73, v115 offset:16900
	ds_read_b32 v74, v115 offset:17160
	ds_read_b32 v75, v115 offset:17420
	ds_read_b32 v76, v115 offset:17680
	ds_read_b32 v77, v115 offset:17940
	ds_read_b32 v78, v115 offset:18200
	ds_read_b32 v79, v115 offset:18460
	ds_read_b32 v26, v115 offset:16768
	ds_read_b32 v27, v115 offset:17028
	ds_read_b32 v28, v115 offset:17288
	ds_read_b32 v29, v115 offset:17548
	ds_read_b32 v30, v115 offset:17808
	ds_read_b32 v31, v115 offset:18068
	ds_read_b32 v32, v115 offset:18328
	ds_read_b32 v33, v115 offset:18588
	s_waitcnt lgkmcnt(8)
	v_cvt_pk_bf16_f32 v124, v72, v73
	v_cvt_pk_bf16_f32 v125, v74, v75
	v_cvt_pk_bf16_f32 v126, v76, v77
	v_cvt_pk_bf16_f32 v127, v78, v79
	global_store_dwordx4 v120, v[124:127], s[0:1]
	s_waitcnt lgkmcnt(0)
	v_cvt_pk_bf16_f32 v128, v26, v27
	v_cvt_pk_bf16_f32 v129, v28, v29
	v_cvt_pk_bf16_f32 v130, v30, v31
	v_cvt_pk_bf16_f32 v131, v32, v33
	global_store_dwordx4 v121, v[128:131], s[0:1]
	s_add_i32 s59, s2, 0x600
	s_cmp_lt_u32 s59, 0x1000
	s_cbranch_scc0 .Lcv_sd3
	s_lshr_b32 s60, s59, 11
	s_bfe_u32 s71, s59, 0x40007
	s_bfe_u32 s35, s59, 0x30004
	s_and_b32 s51, s59, 15
	s_lshl_b32 s0, s36, 4
	s_add_i32 s71, s71, s0
	s_lshl_b32 s71, s71, 21
	s_lshl_b32 s0, s51, 17
	s_add_i32 s71, s71, s0
	s_lshl_b32 s0, s35, 8
	s_add_i32 s71, s71, s0
	s_cmp_eq_u32 s60, 0
	s_cselect_b32 s88, s52, s54
	s_cselect_b32 s89, s53, s55
	s_add_u32 s88, s88, s71
	s_addc_u32 s89, s89, 0
	s_mov_b32 s94, 11
	s_branch .Lcv_se3

; __device__ __forceinline__ u16 f2bf(float f) { return (u16)(pack2(f, 0.f) & 0xffffu); }
; __device__ __forceinline__ int tid_() { int t = threadIdx.x; asm volatile("" : "+v"(t)); return t; }
; __device__ __forceinline__ void convT_tile(const float* __restrict__ src, int lds, int k0, int c0, u16* __restrict__ dst, int Kd,
;                                            int rbase, int mode, int which, unsigned char* smem, const float* __restrict__ kscale = nullptr) {
;   float* tile = (float*)smem;
;   const int t = tid_();
;   float4 v4[4];
; #pragma unroll
;   for (int i = 0; i < 4; ++i) {
;     const f32x4 w_ = __builtin_nontemporal_load((const f32x4*)(src + (size_t)(k0 + i * 16 + (t >> 4)) * lds + c0 + (t & 15) * 4));
;     v4[i] = make_float4(w_[0], w_[1], w_[2], w_[3]);
;   }
; #pragma unroll
;   for (int i = 0; i < 4; ++i) {
;     const int kk = i * 16 + (t >> 4), cc = (t & 15) * 4;
;     const float sc = kscale ? kscale[k0 + kk] : 1.f;
;     tile[kk * 65 + cc + 0] = v4[i].x * sc; tile[kk * 65 + cc + 1] = v4[i].y * sc;
;     tile[kk * 65 + cc + 2] = v4[i].z * sc; tile[kk * 65 + cc + 3] = v4[i].w * sc;
;   }
;   __syncthreads();
; #pragma unroll
;   for (int i = 0; i < 16; ++i) {
;     const int cc = i * 4 + (t >> 6), kk = t & 63;
;     int row;
;     if (mode == 0) row = rbase + cc;
;     else { const int f = c0 + cc; row = (((f >> 4) * 2 + which) << 4) + (f & 15); }
;     dst[(size_t)row * Kd + k0 + kk] = f2bf(tile[kk * 65 + cc]);
;   }
;   __syncthreads();
; }
; __device__ __forceinline__ void conv_item(const Params& p, int it, unsigned char* smem) {
;     ...
;   if (r < 4096) {
;     const int which = r >> 11, r2 = r & 2047, e = r2 >> 7, r3 = r2 & 127, ct = r3 >> 4, kt = r3 & 15;
;     const float* src = (which ? p.w_up : p.w_gate) + (size_t)(l * 16 + e) * 1024 * 512;
;     convT_tile(src, 512, kt * 64, ct * 64, p.WguT + (size_t)(l * 16 + e) * 1024 * 1024, 1024, 0, 1, which, smem);
;     return;
;   }
;   r -= 4096;
;   {
;     const int e = r >> 7, r3 = r & 127, ct = r3 >> 3, kt = r3 & 7;
;     convT_tile(p.w_down + (size_t)(l * 16 + e) * 512 * 1024, 1024, kt * 64, ct * 64, p.WdT + (size_t)(l * 16 + e) * 1024 * 512, 512, ct * 64, 0, 0, smem);
;   }
.Lcv_se3:
	v_lshl_add_u32 v116, v98, s94, v102
	v_lshl_add_u32 v117, v99, s94, v102
	v_lshl_add_u32 v118, v100, s94, v102
	v_lshl_add_u32 v119, v101, s94, v102
	global_load_dwordx4 v[148:151], v116, s[88:89] nt
	global_load_dwordx4 v[152:155], v117, s[88:89] nt
	global_load_dwordx4 v[156:159], v118, s[88:89] nt
	global_load_dwordx4 v[160:163], v119, s[88:89] nt
	s_add_i32 s59, s2, 0x400
	s_cmp_lt_u32 s59, 0x1000
	s_cbranch_scc0 .Lcv_dd2
	s_lshr_b32 s60, s59, 11
	s_bfe_u32 s71, s59, 0x40007
	s_bfe_u32 s35, s59, 0x30004
	s_and_b32 s51, s59, 15
	s_lshl_b32 s0, s36, 4
	s_add_i32 s71, s71, s0
	s_lshl_b32 s71, s71, 21
	s_lshl_b32 s35, s35, 7
	s_lshl_b32 s60, s60, 4
	s_add_i32 s35, s35, s60
	s_lshl_b32 s35, s35, 11
	s_add_i32 s71, s71, s35
	s_lshl_b32 s51, s51, 7
	s_add_i32 s71, s71, s51
	s_add_u32 s0, s98, s71
	s_addc_u32 s1, s99, 0
	v_mov_b32_e32 v120, v103
	v_mov_b32_e32 v121, v104
	s_branch .Lcv_de2

; __device__ __forceinline__ u16 f2bf(float f) { return (u16)(pack2(f, 0.f) & 0xffffu); }
; __device__ __forceinline__ int tid_() { int t = threadIdx.x; asm volatile("" : "+v"(t)); return t; }
; __device__ __forceinline__ void convT_tile(const float* __restrict__ src, int lds, int k0, int c0, u16* __restrict__ dst, int Kd,
;                                            int rbase, int mode, int which, unsigned char* smem, const float* __restrict__ kscale = nullptr) {
;   float* tile = (float*)smem;
;   const int t = tid_();
;   float4 v4[4];
; #pragma unroll
;   for (int i = 0; i < 4; ++i) {
;     const f32x4 w_ = __builtin_nontemporal_load((const f32x4*)(src + (size_t)(k0 + i * 16 + (t >> 4)) * lds + c0 + (t & 15) * 4));
;     v4[i] = make_float4(w_[0], w_[1], w_[2], w_[3]);
;   }
; #pragma unroll
;   for (int i = 0; i < 4; ++i) {
;     const int kk = i * 16 + (t >> 4), cc = (t & 15) * 4;
;     const float sc = kscale ? kscale[k0 + kk] : 1.f;
;     tile[kk * 65 + cc + 0] = v4[i].x * sc; tile[kk * 65 + cc + 1] = v4[i].y * sc;
;     tile[kk * 65 + cc + 2] = v4[i].z * sc; tile[kk * 65 + cc + 3] = v4[i].w * sc;
;   }
;   __syncthreads();
; #pragma unroll
;   for (int i = 0; i < 16; ++i) {
;     const int cc = i * 4 + (t >> 6), kk = t & 63;
;     int row;
;     if (mode == 0) row = rbase + cc;
;     else { const int f = c0 + cc; row = (((f >> 4) * 2 + which) << 4) + (f & 15); }
;     dst[(size_t)row * Kd + k0 + kk] = f2bf(tile[kk * 65 + cc]);
;   }
;   __syncthreads();
; }
.Lcv_de2:
	s_waitcnt vmcnt(6)
	ds_write2_b32 v107, v132, v133 offset1:1
	ds_write2_b32 v107, v134, v135 offset0:2 offset1:3
	ds_write2_b32 v108, v136, v137 offset1:1
	ds_write2_b32 v108, v138, v139 offset0:2 offset1:3
	ds_write2_b32 v109, v140, v141 offset1:1
	ds_write2_b32 v109, v142, v143 offset0:2 offset1:3
	ds_write2_b32 v110, v144, v145 offset1:1
	ds_write2_b32 v110, v146, v147 offset0:2 offset1:3
	s_waitcnt lgkmcnt(0)
	s_barrier
	ds_read_b32 v72, v115 offset:0
	ds_read_b32 v73, v115 offset:260
	ds_read_b32 v74, v115 offset:520
	ds_read_b32 v75, v115 offset:780
	ds_read_b32 v76, v115 offset:1040
	ds_read_b32 v77, v115 offset:1300
	ds_read_b32 v78, v115 offset:1560
	ds_read_b32 v79, v115 offset:1820
	ds_read_b32 v26, v115 offset:128
	ds_read_b32 v27, v115 offset:388
	ds_read_b32 v28, v115 offset:648
	ds_read_b32 v29, v115 offset:908
	ds_read_b32 v30, v115 offset:1168
	ds_read_b32 v31, v115 offset:1428
	ds_read_b32 v32, v115 offset:1688
	ds_read_b32 v33, v115 offset:1948
	s_waitcnt lgkmcnt(8)
	v_cvt_pk_bf16_f32 v124, v72, v73
	v_cvt_pk_bf16_f32 v125, v74, v75
	v_cvt_pk_bf16_f32 v126, v76, v77
	v_cvt_pk_bf16_f32 v127, v78, v79
	global_store_dwordx4 v120, v[124:127], s[0:1]
	s_waitcnt lgkmcnt(0)
	v_cvt_pk_bf16_f32 v128, v26, v27
	v_cvt_pk_bf16_f32 v129, v28, v29
	v_cvt_pk_bf16_f32 v130, v30, v31
	v_cvt_pk_bf16_f32 v131, v32, v33
	global_store_dwordx4 v121, v[128:131], s[0:1]
	s_add_i32 s59, s2, 0x800
	s_cmp_lt_u32 s59, 0x1000
	s_cbranch_scc0 .Lcv_sd4
	s_lshr_b32 s60, s59, 11
	s_bfe_u32 s71, s59, 0x40007
	s_bfe_u32 s35, s59, 0x30004
	s_and_b32 s51, s59, 15
	s_lshl_b32 s0, s36, 4
	s_add_i32 s71, s71, s0
	s_lshl_b32 s71, s71, 21
	s_lshl_b32 s0, s51, 17
	s_add_i32 s71, s71, s0
	s_lshl_b32 s0, s35, 8
	s_add_i32 s71, s71, s0
	s_cmp_eq_u32 s60, 0
	s_cselect_b32 s88, s52, s54
	s_cselect_b32 s89, s53, s55
	s_add_u32 s88, s88, s71
	s_addc_u32 s89, s89, 0
	s_mov_b32 s94, 11
	s_branch .Lcv_se4

; __device__ __forceinline__ u16 f2bf(float f) { return (u16)(pack2(f, 0.f) & 0xffffu); }
; __device__ __forceinline__ int tid_() { int t = threadIdx.x; asm volatile("" : "+v"(t)); return t; }
; __device__ __forceinline__ void convT_tile(const float* __restrict__ src, int lds, int k0, int c0, u16* __restrict__ dst, int Kd,
;                                            int rbase, int mode, int which, unsigned char* smem, const float* __restrict__ kscale = nullptr) {
;   float* tile = (float*)smem;
;   const int t = tid_();
;   float4 v4[4];
; #pragma unroll
;   for (int i = 0; i < 4; ++i) {
;     const f32x4 w_ = __builtin_nontemporal_load((const f32x4*)(src + (size_t)(k0 + i * 16 + (t >> 4)) * lds + c0 + (t & 15) * 4));
;     v4[i] = make_float4(w_[0], w_[1], w_[2], w_[3]);
;   }
; #pragma unroll
;   for (int i = 0; i < 4; ++i) {
;     const int kk = i * 16 + (t >> 4), cc = (t & 15) * 4;
;     const float sc = kscale ? kscale[k0 + kk] : 1.f;
;     tile[kk * 65 + cc + 0] = v4[i].x * sc; tile[kk * 65 + cc + 1] = v4[i].y * sc;
;     tile[kk * 65 + cc + 2] = v4[i].z * sc; tile[kk * 65 + cc + 3] = v4[i].w * sc;
;   }
;   __syncthreads();
; #pragma unroll
;   for (int i = 0; i < 16; ++i) {
;     const int cc = i * 4 + (t >> 6), kk = t & 63;
;     int row;
;     if (mode == 0) row = rbase + cc;
;     else { const int f = c0 + cc; row = (((f >> 4) * 2 + which) << 4) + (f & 15); }
;     dst[(size_t)row * Kd + k0 + kk] = f2bf(tile[kk * 65 + cc]);
;   }
;   __syncthreads();
; }
; __device__ __forceinline__ void conv_item(const Params& p, int it, unsigned char* smem) {
;     ...
;   if (r < 4096) {
;     const int which = r >> 11, r2 = r & 2047, e = r2 >> 7, r3 = r2 & 127, ct = r3 >> 4, kt = r3 & 15;
;     const float* src = (which ? p.w_up : p.w_gate) + (size_t)(l * 16 + e) * 1024 * 512;
;     convT_tile(src, 512, kt * 64, ct * 64, p.WguT + (size_t)(l * 16 + e) * 1024 * 1024, 1024, 0, 1, which, smem);
;     return;
;   }
;   r -= 4096;
;   {
;     const int e = r >> 7, r3 = r & 127, ct = r3 >> 3, kt = r3 & 7;
;     convT_tile(p.w_down + (size_t)(l * 16 + e) * 512 * 1024, 1024, kt * 64, ct * 64, p.WdT + (size_t)(l * 16 + e) * 1024 * 512, 512, ct * 64, 0, 0, smem);
;   }
.Lcv_se4:
	v_lshl_add_u32 v116, v98, s94, v102
	v_lshl_add_u32 v117, v99, s94, v102
	v_lshl_add_u32 v118, v100, s94, v102
	v_lshl_add_u32 v119, v101, s94, v102
	global_load_dwordx4 v[132:135], v116, s[88:89] nt
	global_load_dwordx4 v[136:139], v117, s[88:89] nt
	global_load_dwordx4 v[140:143], v118, s[88:89] nt
	global_load_dwordx4 v[144:147], v119, s[88:89] nt
	s_add_i32 s59, s2, 0x600
	s_cmp_lt_u32 s59, 0x1000
	s_cbranch_scc0 .Lcv_dd3
	s_lshr_b32 s60, s59, 11
	s_bfe_u32 s71, s59, 0x40007
	s_bfe_u32 s35, s59, 0x30004
	s_and_b32 s51, s59, 15
	s_lshl_b32 s0, s36, 4
	s_add_i32 s71, s71, s0
	s_lshl_b32 s71, s71, 21
	s_lshl_b32 s35, s35, 7
	s_lshl_b32 s60, s60, 4
	s_add_i32 s35, s35, s60
	s_lshl_b32 s35, s35, 11
	s_add_i32 s71, s71, s35
	s_lshl_b32 s51, s51, 7
	s_add_i32 s71, s71, s51
	s_add_u32 s0, s98, s71
	s_addc_u32 s1, s99, 0
	v_mov_b32_e32 v120, v103
	v_mov_b32_e32 v121, v104
	s_branch .Lcv_de3

; __device__ __forceinline__ u16 f2bf(float f) { return (u16)(pack2(f, 0.f) & 0xffffu); }
; __device__ __forceinline__ int tid_() { int t = threadIdx.x; asm volatile("" : "+v"(t)); return t; }
; __device__ __forceinline__ void convT_tile(const float* __restrict__ src, int lds, int k0, int c0, u16* __restrict__ dst, int Kd,
;                                            int rbase, int mode, int which, unsigned char* smem, const float* __restrict__ kscale = nullptr) {
;   float* tile = (float*)smem;
;   const int t = tid_();
;   float4 v4[4];
; #pragma unroll
;   for (int i = 0; i < 4; ++i) {
;     const f32x4 w_ = __builtin_nontemporal_load((const f32x4*)(src + (size_t)(k0 + i * 16 + (t >> 4)) * lds + c0 + (t & 15) * 4));
;     v4[i] = make_float4(w_[0], w_[1], w_[2], w_[3]);
;   }
; #pragma unroll
;   for (int i = 0; i < 4; ++i) {
;     const int kk = i * 16 + (t >> 4), cc = (t & 15) * 4;
;     const float sc = kscale ? kscale[k0 + kk] : 1.f;
;     tile[kk * 65 + cc + 0] = v4[i].x * sc; tile[kk * 65 + cc + 1] = v4[i].y * sc;
;     tile[kk * 65 + cc + 2] = v4[i].z * sc; tile[kk * 65 + cc + 3] = v4[i].w * sc;
;   }
;   __syncthreads();
; #pragma unroll
;   for (int i = 0; i < 16; ++i) {
;     const int cc = i * 4 + (t >> 6), kk = t & 63;
;     int row;
;     if (mode == 0) row = rbase + cc;
;     else { const int f = c0 + cc; row = (((f >> 4) * 2 + which) << 4) + (f & 15); }
;     dst[(size_t)row * Kd + k0 + kk] = f2bf(tile[kk * 65 + cc]);
;   }
;   __syncthreads();
; }
.Lcv_de3:
	s_waitcnt vmcnt(6)
	ds_write2_b32 v111, v148, v149 offset1:1
	ds_write2_b32 v111, v150, v151 offset0:2 offset1:3
	ds_write2_b32 v112, v152, v153 offset1:1
	ds_write2_b32 v112, v154, v155 offset0:2 offset1:3
	ds_write2_b32 v113, v156, v157 offset1:1
	ds_write2_b32 v113, v158, v159 offset0:2 offset1:3
	ds_write2_b32 v114, v160, v161 offset1:1
	ds_write2_b32 v114, v162, v163 offset0:2 offset1:3
	s_waitcnt lgkmcnt(0)
	s_barrier
	ds_read_b32 v72, v115 offset:16640
	ds_read_b32 v73, v115 offset:16900
	ds_read_b32 v74, v115 offset:17160
	ds_read_b32 v75, v115 offset:17420
	ds_read_b32 v76, v115 offset:17680
	ds_read_b32 v77, v115 offset:17940
	ds_read_b32 v78, v115 offset:18200
	ds_read_b32 v79, v115 offset:18460
	ds_read_b32 v26, v115 offset:16768
	ds_read_b32 v27, v115 offset:17028
	ds_read_b32 v28, v115 offset:17288
	ds_read_b32 v29, v115 offset:17548
	ds_read_b32 v30, v115 offset:17808
	ds_read_b32 v31, v115 offset:18068
	ds_read_b32 v32, v115 offset:18328
	ds_read_b32 v33, v115 offset:18588
	s_waitcnt lgkmcnt(8)
	v_cvt_pk_bf16_f32 v124, v72, v73
	v_cvt_pk_bf16_f32 v125, v74, v75
	v_cvt_pk_bf16_f32 v126, v76, v77
	v_cvt_pk_bf16_f32 v127, v78, v79
	global_store_dwordx4 v120, v[124:127], s[0:1]
	s_waitcnt lgkmcnt(0)
	v_cvt_pk_bf16_f32 v128, v26, v27
	v_cvt_pk_bf16_f32 v129, v28, v29
	v_cvt_pk_bf16_f32 v130, v30, v31
	v_cvt_pk_bf16_f32 v131, v32, v33
	global_store_dwordx4 v121, v[128:131], s[0:1]
	s_add_i32 s59, s2, 0xa00
	s_cmp_lt_u32 s59, 0x1000
	s_cbranch_scc0 .Lcv_sd5
	s_lshr_b32 s60, s59, 11
	s_bfe_u32 s71, s59, 0x40007
	s_bfe_u32 s35, s59, 0x30004
	s_and_b32 s51, s59, 15
	s_lshl_b32 s0, s36, 4
	s_add_i32 s71, s71, s0
	s_lshl_b32 s71, s71, 21
	s_lshl_b32 s0, s51, 17
	s_add_i32 s71, s71, s0
	s_lshl_b32 s0, s35, 8
	s_add_i32 s71, s71, s0
	s_cmp_eq_u32 s60, 0
	s_cselect_b32 s88, s52, s54
	s_cselect_b32 s89, s53, s55
	s_add_u32 s88, s88, s71
	s_addc_u32 s89, s89, 0
	s_mov_b32 s94, 11
	s_branch .Lcv_se5

; __device__ __forceinline__ u16 f2bf(float f) { return (u16)(pack2(f, 0.f) & 0xffffu); }
; __device__ __forceinline__ int tid_() { int t = threadIdx.x; asm volatile("" : "+v"(t)); return t; }
; __device__ __forceinline__ void convT_tile(const float* __restrict__ src, int lds, int k0, int c0, u16* __restrict__ dst, int Kd,
;                                            int rbase, int mode, int which, unsigned char* smem, const float* __restrict__ kscale = nullptr) {
;   float* tile = (float*)smem;
;   const int t = tid_();
;   float4 v4[4];
; #pragma unroll
;   for (int i = 0; i < 4; ++i) {
;     const f32x4 w_ = __builtin_nontemporal_load((const f32x4*)(src + (size_t)(k0 + i * 16 + (t >> 4)) * lds + c0 + (t & 15) * 4));
;     v4[i] = make_float4(w_[0], w_[1], w_[2], w_[3]);
;   }
; #pragma unroll
;   for (int i = 0; i < 4; ++i) {
;     const int kk = i * 16 + (t >> 4), cc = (t & 15) * 4;
;     const float sc = kscale ? kscale[k0 + kk] : 1.f;
;     tile[kk * 65 + cc + 0] = v4[i].x * sc; tile[kk * 65 + cc + 1] = v4[i].y * sc;
;     tile[kk * 65 + cc + 2] = v4[i].z * sc; tile[kk * 65 + cc + 3] = v4[i].w * sc;
;   }
;   __syncthreads();
; #pragma unroll
;   for (int i = 0; i < 16; ++i) {
;     const int cc = i * 4 + (t >> 6), kk = t & 63;
;     int row;
;     if (mode == 0) row = rbase + cc;
;     else { const int f = c0 + cc; row = (((f >> 4) * 2 + which) << 4) + (f & 15); }
;     dst[(size_t)row * Kd + k0 + kk] = f2bf(tile[kk * 65 + cc]);
;   }
;   __syncthreads();
; }
; __device__ __forceinline__ void conv_item(const Params& p, int it, unsigned char* smem) {
;     ...
;   if (r < 4096) {
;     const int which = r >> 11, r2 = r & 2047, e = r2 >> 7, r3 = r2 & 127, ct = r3 >> 4, kt = r3 & 15;
;     const float* src = (which ? p.w_up : p.w_gate) + (size_t)(l * 16 + e) * 1024 * 512;
;     convT_tile(src, 512, kt * 64, ct * 64, p.WguT + (size_t)(l * 16 + e) * 1024 * 1024, 1024, 0, 1, which, smem);
;     return;
;   }
;   r -= 4096;
;   {
;     const int e = r >> 7, r3 = r & 127, ct = r3 >> 3, kt = r3 & 7;
;     convT_tile(p.w_down + (size_t)(l * 16 + e) * 512 * 1024, 1024, kt * 64, ct * 64, p.WdT + (size_t)(l * 16 + e) * 1024 * 512, 512, ct * 64, 0, 0, smem);
;   }
.Lcv_se5:
	v_lshl_add_u32 v116, v98, s94, v102
	v_lshl_add_u32 v117, v99, s94, v102
	v_lshl_add_u32 v118, v100, s94, v102
	v_lshl_add_u32 v119, v101, s94, v102
	global_load_dwordx4 v[148:151], v116, s[88:89] nt
	global_load_dwordx4 v[152:155], v117, s[88:89] nt
	global_load_dwordx4 v[156:159], v118, s[88:89] nt
	global_load_dwordx4 v[160:163], v119, s[88:89] nt
	s_add_i32 s59, s2, 0x800
	s_cmp_lt_u32 s59, 0x1000
	s_cbranch_scc0 .Lcv_dd4
	s_lshr_b32 s60, s59, 11
	s_bfe_u32 s71, s59, 0x40007
	s_bfe_u32 s35, s59, 0x30004
	s_and_b32 s51, s59, 15
	s_lshl_b32 s0, s36, 4
	s_add_i32 s71, s71, s0
	s_lshl_b32 s71, s71, 21
	s_lshl_b32 s35, s35, 7
	s_lshl_b32 s60, s60, 4
	s_add_i32 s35, s35, s60
	s_lshl_b32 s35, s35, 11
	s_add_i32 s71, s71, s35
	s_lshl_b32 s51, s51, 7
	s_add_i32 s71, s71, s51
	s_add_u32 s0, s98, s71
	s_addc_u32 s1, s99, 0
	v_mov_b32_e32 v120, v103
	v_mov_b32_e32 v121, v104
	s_branch .Lcv_de4

; __device__ __forceinline__ u16 f2bf(float f) { return (u16)(pack2(f, 0.f) & 0xffffu); }
; __device__ __forceinline__ int tid_() { int t = threadIdx.x; asm volatile("" : "+v"(t)); return t; }
; __device__ __forceinline__ void convT_tile(const float* __restrict__ src, int lds, int k0, int c0, u16* __restrict__ dst, int Kd,
;                                            int rbase, int mode, int which, unsigned char* smem, const float* __restrict__ kscale = nullptr) {
;   float* tile = (float*)smem;
;   const int t = tid_();
;   float4 v4[4];
; #pragma unroll
;   for (int i = 0; i < 4; ++i) {
;     const f32x4 w_ = __builtin_nontemporal_load((const f32x4*)(src + (size_t)(k0 + i * 16 + (t >> 4)) * lds + c0 + (t & 15) * 4));
;     v4[i] = make_float4(w_[0], w_[1], w_[2], w_[3]);
;   }
; #pragma unroll
;   for (int i = 0; i < 4; ++i) {
;     const int kk = i * 16 + (t >> 4), cc = (t & 15) * 4;
;     const float sc = kscale ? kscale[k0 + kk] : 1.f;
;     tile[kk * 65 + cc + 0] = v4[i].x * sc; tile[kk * 65 + cc + 1] = v4[i].y * sc;
;     tile[kk * 65 + cc + 2] = v4[i].z * sc; tile[kk * 65 + cc + 3] = v4[i].w * sc;
;   }
;   __syncthreads();
; #pragma unroll
;   for (int i = 0; i < 16; ++i) {
;     const int cc = i * 4 + (t >> 6), kk = t & 63;
;     int row;
;     if (mode == 0) row = rbase + cc;
;     else { const int f = c0 + cc; row = (((f >> 4) * 2 + which) << 4) + (f & 15); }
;     dst[(size_t)row * Kd + k0 + kk] = f2bf(tile[kk * 65 + cc]);
;   }
;   __syncthreads();
; }
.Lcv_de4:
	s_waitcnt vmcnt(6)
	ds_write2_b32 v107, v132, v133 offset1:1
	ds_write2_b32 v107, v134, v135 offset0:2 offset1:3
	ds_write2_b32 v108, v136, v137 offset1:1
	ds_write2_b32 v108, v138, v139 offset0:2 offset1:3
	ds_write2_b32 v109, v140, v141 offset1:1
	ds_write2_b32 v109, v142, v143 offset0:2 offset1:3
	ds_write2_b32 v110, v144, v145 offset1:1
	ds_write2_b32 v110, v146, v147 offset0:2 offset1:3
	s_waitcnt lgkmcnt(0)
	s_barrier
	ds_read_b32 v72, v115 offset:0
	ds_read_b32 v73, v115 offset:260
	ds_read_b32 v74, v115 offset:520
	ds_read_b32 v75, v115 offset:780
	ds_read_b32 v76, v115 offset:1040
	ds_read_b32 v77, v115 offset:1300
	ds_read_b32 v78, v115 offset:1560
	ds_read_b32 v79, v115 offset:1820
	ds_read_b32 v26, v115 offset:128
	ds_read_b32 v27, v115 offset:388
	ds_read_b32 v28, v115 offset:648
	ds_read_b32 v29, v115 offset:908
	ds_read_b32 v30, v115 offset:1168
	ds_read_b32 v31, v115 offset:1428
	ds_read_b32 v32, v115 offset:1688
	ds_read_b32 v33, v115 offset:1948
	s_waitcnt lgkmcnt(8)
	v_cvt_pk_bf16_f32 v124, v72, v73
	v_cvt_pk_bf16_f32 v125, v74, v75
	v_cvt_pk_bf16_f32 v126, v76, v77
	v_cvt_pk_bf16_f32 v127, v78, v79
	global_store_dwordx4 v120, v[124:127], s[0:1]
	s_waitcnt lgkmcnt(0)
	v_cvt_pk_bf16_f32 v128, v26, v27
	v_cvt_pk_bf16_f32 v129, v28, v29
	v_cvt_pk_bf16_f32 v130, v30, v31
	v_cvt_pk_bf16_f32 v131, v32, v33
	global_store_dwordx4 v121, v[128:131], s[0:1]
	s_add_i32 s59, s2, 0xc00
	s_cmp_lt_u32 s59, 0x1000
	s_cbranch_scc0 .Lcv_sd6
	s_lshr_b32 s60, s59, 11
	s_bfe_u32 s71, s59, 0x40007
	s_bfe_u32 s35, s59, 0x30004
	s_and_b32 s51, s59, 15
	s_lshl_b32 s0, s36, 4
	s_add_i32 s71, s71, s0
	s_lshl_b32 s71, s71, 21
	s_lshl_b32 s0, s51, 17
	s_add_i32 s71, s71, s0
	s_lshl_b32 s0, s35, 8
	s_add_i32 s71, s71, s0
	s_cmp_eq_u32 s60, 0
	s_cselect_b32 s88, s52, s54
	s_cselect_b32 s89, s53, s55
	s_add_u32 s88, s88, s71
	s_addc_u32 s89, s89, 0
	s_mov_b32 s94, 11
	s_branch .Lcv_se6

; __device__ __forceinline__ u16 f2bf(float f) { return (u16)(pack2(f, 0.f) & 0xffffu); }
; __device__ __forceinline__ int tid_() { int t = threadIdx.x; asm volatile("" : "+v"(t)); return t; }
; __device__ __forceinline__ void convT_tile(const float* __restrict__ src, int lds, int k0, int c0, u16* __restrict__ dst, int Kd,
;                                            int rbase, int mode, int which, unsigned char* smem, const float* __restrict__ kscale = nullptr) {
;   float* tile = (float*)smem;
;   const int t = tid_();
;   float4 v4[4];
; #pragma unroll
;   for (int i = 0; i < 4; ++i) {
;     const f32x4 w_ = __builtin_nontemporal_load((const f32x4*)(src + (size_t)(k0 + i * 16 + (t >> 4)) * lds + c0 + (t & 15) * 4));
;     v4[i] = make_float4(w_[0], w_[1], w_[2], w_[3]);
;   }
; #pragma unroll
;   for (int i = 0; i < 4; ++i) {
;     const int kk = i * 16 + (t >> 4), cc = (t & 15) * 4;
;     const float sc = kscale ? kscale[k0 + kk] : 1.f;
;     tile[kk * 65 + cc + 0] = v4[i].x * sc; tile[kk * 65 + cc + 1] = v4[i].y * sc;
;     tile[kk * 65 + cc + 2] = v4[i].z * sc; tile[kk * 65 + cc + 3] = v4[i].w * sc;
;   }
;   __syncthreads();
; #pragma unroll
;   for (int i = 0; i < 16; ++i) {
;     const int cc = i * 4 + (t >> 6), kk = t & 63;
;     int row;
;     if (mode == 0) row = rbase + cc;
;     else { const int f = c0 + cc; row = (((f >> 4) * 2 + which) << 4) + (f & 15); }
;     dst[(size_t)row * Kd + k0 + kk] = f2bf(tile[kk * 65 + cc]);
;   }
;   __syncthreads();
; }
; __device__ __forceinline__ void conv_item(const Params& p, int it, unsigned char* smem) {
;     ...
;   if (r < 4096) {
;     const int which = r >> 11, r2 = r & 2047, e = r2 >> 7, r3 = r2 & 127, ct = r3 >> 4, kt = r3 & 15;
;     const float* src = (which ? p.w_up : p.w_gate) + (size_t)(l * 16 + e) * 1024 * 512;
;     convT_tile(src, 512, kt * 64, ct * 64, p.WguT + (size_t)(l * 16 + e) * 1024 * 1024, 1024, 0, 1, which, smem);
;     return;
;   }
;   r -= 4096;
;   {
;     const int e = r >> 7, r3 = r & 127, ct = r3 >> 3, kt = r3 & 7;
;     convT_tile(p.w_down + (size_t)(l * 16 + e) * 512 * 1024, 1024, kt * 64, ct * 64, p.WdT + (size_t)(l * 16 + e) * 1024 * 512, 512, ct * 64, 0, 0, smem);
;   }
.Lcv_se6:
	v_lshl_add_u32 v116, v98, s94, v102
	v_lshl_add_u32 v117, v99, s94, v102
	v_lshl_add_u32 v118, v100, s94, v102
	v_lshl_add_u32 v119, v101, s94, v102
	global_load_dwordx4 v[132:135], v116, s[88:89] nt
	global_load_dwordx4 v[136:139], v117, s[88:89] nt
	global_load_dwordx4 v[140:143], v118, s[88:89] nt
	global_load_dwordx4 v[144:147], v119, s[88:89] nt
	s_add_i32 s59, s2, 0xa00
	s_cmp_lt_u32 s59, 0x1000
	s_cbranch_scc0 .Lcv_dd5
	s_lshr_b32 s60, s59, 11
	s_bfe_u32 s71, s59, 0x40007
	s_bfe_u32 s35, s59, 0x30004
	s_and_b32 s51, s59, 15
	s_lshl_b32 s0, s36, 4
	s_add_i32 s71, s71, s0
	s_lshl_b32 s71, s71, 21
	s_lshl_b32 s35, s35, 7
	s_lshl_b32 s60, s60, 4
	s_add_i32 s35, s35, s60
	s_lshl_b32 s35, s35, 11
	s_add_i32 s71, s71, s35
	s_lshl_b32 s51, s51, 7
	s_add_i32 s71, s71, s51
	s_add_u32 s0, s98, s71
	s_addc_u32 s1, s99, 0
	v_mov_b32_e32 v120, v103
	v_mov_b32_e32 v121, v104
	s_branch .Lcv_de5

; __device__ __forceinline__ u16 f2bf(float f) { return (u16)(pack2(f, 0.f) & 0xffffu); }
; __device__ __forceinline__ int tid_() { int t = threadIdx.x; asm volatile("" : "+v"(t)); return t; }
; __device__ __forceinline__ void convT_tile(const float* __restrict__ src, int lds, int k0, int c0, u16* __restrict__ dst, int Kd,
;                                            int rbase, int mode, int which, unsigned char* smem, const float* __restrict__ kscale = nullptr) {
;   float* tile = (float*)smem;
;   const int t = tid_();
;   float4 v4[4];
; #pragma unroll
;   for (int i = 0; i < 4; ++i) {
;     const f32x4 w_ = __builtin_nontemporal_load((const f32x4*)(src + (size_t)(k0 + i * 16 + (t >> 4)) * lds + c0 + (t & 15) * 4));
;     v4[i] = make_float4(w_[0], w_[1], w_[2], w_[3]);
;   }
; #pragma unroll
;   for (int i = 0; i < 4; ++i) {
;     const int kk = i * 16 + (t >> 4), cc = (t & 15) * 4;
;     const float sc = kscale ? kscale[k0 + kk] : 1.f;
;     tile[kk * 65 + cc + 0] = v4[i].x * sc; tile[kk * 65 + cc + 1] = v4[i].y * sc;
;     tile[kk * 65 + cc + 2] = v4[i].z * sc; tile[kk * 65 + cc + 3] = v4[i].w * sc;
;   }
;   __syncthreads();
; #pragma unroll
;   for (int i = 0; i < 16; ++i) {
;     const int cc = i * 4 + (t >> 6), kk = t & 63;
;     int row;
;     if (mode == 0) row = rbase + cc;
;     else { const int f = c0 + cc; row = (((f >> 4) * 2 + which) << 4) + (f & 15); }
;     dst[(size_t)row * Kd + k0 + kk] = f2bf(tile[kk * 65 + cc]);
;   }
;   __syncthreads();
; }
.Lcv_de5:
	s_waitcnt vmcnt(6)
	ds_write2_b32 v111, v148, v149 offset1:1
	ds_write2_b32 v111, v150, v151 offset0:2 offset1:3
	ds_write2_b32 v112, v152, v153 offset1:1
	ds_write2_b32 v112, v154, v155 offset0:2 offset1:3
	ds_write2_b32 v113, v156, v157 offset1:1
	ds_write2_b32 v113, v158, v159 offset0:2 offset1:3
	ds_write2_b32 v114, v160, v161 offset1:1
	ds_write2_b32 v114, v162, v163 offset0:2 offset1:3
	s_waitcnt lgkmcnt(0)
	s_barrier
	ds_read_b32 v72, v115 offset:16640
	ds_read_b32 v73, v115 offset:16900
	ds_read_b32 v74, v115 offset:17160
	ds_read_b32 v75, v115 offset:17420
	ds_read_b32 v76, v115 offset:17680
	ds_read_b32 v77, v115 offset:17940
	ds_read_b32 v78, v115 offset:18200
	ds_read_b32 v79, v115 offset:18460
	ds_read_b32 v26, v115 offset:16768
	ds_read_b32 v27, v115 offset:17028
	ds_read_b32 v28, v115 offset:17288
	ds_read_b32 v29, v115 offset:17548
	ds_read_b32 v30, v115 offset:17808
	ds_read_b32 v31, v115 offset:18068
	ds_read_b32 v32, v115 offset:18328
	ds_read_b32 v33, v115 offset:18588
	s_waitcnt lgkmcnt(8)
	v_cvt_pk_bf16_f32 v124, v72, v73
	v_cvt_pk_bf16_f32 v125, v74, v75
	v_cvt_pk_bf16_f32 v126, v76, v77
	v_cvt_pk_bf16_f32 v127, v78, v79
	global_store_dwordx4 v120, v[124:127], s[0:1]
	s_waitcnt lgkmcnt(0)
	v_cvt_pk_bf16_f32 v128, v26, v27
	v_cvt_pk_bf16_f32 v129, v28, v29
	v_cvt_pk_bf16_f32 v130, v30, v31
	v_cvt_pk_bf16_f32 v131, v32, v33
	global_store_dwordx4 v121, v[128:131], s[0:1]
	s_add_i32 s59, s2, 0xe00
	s_cmp_lt_u32 s59, 0x1000
	s_cbranch_scc0 .Lcv_sd7
	s_lshr_b32 s60, s59, 11
	s_bfe_u32 s71, s59, 0x40007
	s_bfe_u32 s35, s59, 0x30004
	s_and_b32 s51, s59, 15
	s_lshl_b32 s0, s36, 4
	s_add_i32 s71, s71, s0
	s_lshl_b32 s71, s71, 21
	s_lshl_b32 s0, s51, 17
	s_add_i32 s71, s71, s0
	s_lshl_b32 s0, s35, 8
	s_add_i32 s71, s71, s0
	s_cmp_eq_u32 s60, 0
	s_cselect_b32 s88, s52, s54
	s_cselect_b32 s89, s53, s55
	s_add_u32 s88, s88, s71
	s_addc_u32 s89, s89, 0
	s_mov_b32 s94, 11
	s_branch .Lcv_se7

; __device__ __forceinline__ u16 f2bf(float f) { return (u16)(pack2(f, 0.f) & 0xffffu); }
; __device__ __forceinline__ int tid_() { int t = threadIdx.x; asm volatile("" : "+v"(t)); return t; }
; __device__ __forceinline__ void convT_tile(const float* __restrict__ src, int lds, int k0, int c0, u16* __restrict__ dst, int Kd,
;                                            int rbase, int mode, int which, unsigned char* smem, const float* __restrict__ kscale = nullptr) {
;   float* tile = (float*)smem;
;   const int t = tid_();
;   float4 v4[4];
; #pragma unroll
;   for (int i = 0; i < 4; ++i) {
;     const f32x4 w_ = __builtin_nontemporal_load((const f32x4*)(src + (size_t)(k0 + i * 16 + (t >> 4)) * lds + c0 + (t & 15) * 4));
;     v4[i] = make_float4(w_[0], w_[1], w_[2], w_[3]);
;   }
; #pragma unroll
;   for (int i = 0; i < 4; ++i) {
;     const int kk = i * 16 + (t >> 4), cc = (t & 15) * 4;
;     const float sc = kscale ? kscale[k0 + kk] : 1.f;
;     tile[kk * 65 + cc + 0] = v4[i].x * sc; tile[kk * 65 + cc + 1] = v4[i].y * sc;
;     tile[kk * 65 + cc + 2] = v4[i].z * sc; tile[kk * 65 + cc + 3] = v4[i].w * sc;
;   }
;   __syncthreads();
; #pragma unroll
;   for (int i = 0; i < 16; ++i) {
;     const int cc = i * 4 + (t >> 6), kk = t & 63;
;     int row;
;     if (mode == 0) row = rbase + cc;
;     else { const int f = c0 + cc; row = (((f >> 4) * 2 + which) << 4) + (f & 15); }
;     dst[(size_t)row * Kd + k0 + kk] = f2bf(tile[kk * 65 + cc]);
;   }
;   __syncthreads();
; }
; __device__ __forceinline__ void conv_item(const Params& p, int it, unsigned char* smem) {
;     ...
;   if (r < 4096) {
;     const int which = r >> 11, r2 = r & 2047, e = r2 >> 7, r3 = r2 & 127, ct = r3 >> 4, kt = r3 & 15;
;     const float* src = (which ? p.w_up : p.w_gate) + (size_t)(l * 16 + e) * 1024 * 512;
;     convT_tile(src, 512, kt * 64, ct * 64, p.WguT + (size_t)(l * 16 + e) * 1024 * 1024, 1024, 0, 1, which, smem);
;     return;
;   }
;   r -= 4096;
;   {
;     const int e = r >> 7, r3 = r & 127, ct = r3 >> 3, kt = r3 & 7;
;     convT_tile(p.w_down + (size_t)(l * 16 + e) * 512 * 1024, 1024, kt * 64, ct * 64, p.WdT + (size_t)(l * 16 + e) * 1024 * 512, 512, ct * 64, 0, 0, smem);
;   }
.Lcv_se7:
	v_lshl_add_u32 v116, v98, s94, v102
	v_lshl_add_u32 v117, v99, s94, v102
	v_lshl_add_u32 v118, v100, s94, v102
	v_lshl_add_u32 v119, v101, s94, v102
	global_load_dwordx4 v[148:151], v116, s[88:89] nt
	global_load_dwordx4 v[152:155], v117, s[88:89] nt
	global_load_dwordx4 v[156:159], v118, s[88:89] nt
	global_load_dwordx4 v[160:163], v119, s[88:89] nt
	s_add_i32 s59, s2, 0xc00
	s_cmp_lt_u32 s59, 0x1000
	s_cbranch_scc0 .Lcv_dd6
	s_lshr_b32 s60, s59, 11
	s_bfe_u32 s71, s59, 0x40007
	s_bfe_u32 s35, s59, 0x30004
	s_and_b32 s51, s59, 15
	s_lshl_b32 s0, s36, 4
	s_add_i32 s71, s71, s0
	s_lshl_b32 s71, s71, 21
	s_lshl_b32 s35, s35, 7
	s_lshl_b32 s60, s60, 4
	s_add_i32 s35, s35, s60
	s_lshl_b32 s35, s35, 11
	s_add_i32 s71, s71, s35
	s_lshl_b32 s51, s51, 7
	s_add_i32 s71, s71, s51
	s_add_u32 s0, s98, s71
	s_addc_u32 s1, s99, 0
	v_mov_b32_e32 v120, v103
	v_mov_b32_e32 v121, v104
	s_branch .Lcv_de6

; __device__ __forceinline__ u16 f2bf(float f) { return (u16)(pack2(f, 0.f) & 0xffffu); }
; __device__ __forceinline__ int tid_() { int t = threadIdx.x; asm volatile("" : "+v"(t)); return t; }
; __device__ __forceinline__ void convT_tile(const float* __restrict__ src, int lds, int k0, int c0, u16* __restrict__ dst, int Kd,
;                                            int rbase, int mode, int which, unsigned char* smem, const float* __restrict__ kscale = nullptr) {
;   float* tile = (float*)smem;
;   const int t = tid_();
;   float4 v4[4];
; #pragma unroll
;   for (int i = 0; i < 4; ++i) {
;     const f32x4 w_ = __builtin_nontemporal_load((const f32x4*)(src + (size_t)(k0 + i * 16 + (t >> 4)) * lds + c0 + (t & 15) * 4));
;     v4[i] = make_float4(w_[0], w_[1], w_[2], w_[3]);
;   }
; #pragma unroll
;   for (int i = 0; i < 4; ++i) {
;     const int kk = i * 16 + (t >> 4), cc = (t & 15) * 4;
;     const float sc = kscale ? kscale[k0 + kk] : 1.f;
;     tile[kk * 65 + cc + 0] = v4[i].x * sc; tile[kk * 65 + cc + 1] = v4[i].y * sc;
;     tile[kk * 65 + cc + 2] = v4[i].z * sc; tile[kk * 65 + cc + 3] = v4[i].w * sc;
;   }
;   __syncthreads();
; #pragma unroll
;   for (int i = 0; i < 16; ++i) {
;     const int cc = i * 4 + (t >> 6), kk = t & 63;
;     int row;
;     if (mode == 0) row = rbase + cc;
;     else { const int f = c0 + cc; row = (((f >> 4) * 2 + which) << 4) + (f & 15); }
;     dst[(size_t)row * Kd + k0 + kk] = f2bf(tile[kk * 65 + cc]);
;   }
;   __syncthreads();
; }
.Lcv_de6:
	s_waitcnt vmcnt(6)
	ds_write2_b32 v107, v132, v133 offset1:1
	ds_write2_b32 v107, v134, v135 offset0:2 offset1:3
	ds_write2_b32 v108, v136, v137 offset1:1
	ds_write2_b32 v108, v138, v139 offset0:2 offset1:3
	ds_write2_b32 v109, v140, v141 offset1:1
	ds_write2_b32 v109, v142, v143 offset0:2 offset1:3
	ds_write2_b32 v110, v144, v145 offset1:1
	ds_write2_b32 v110, v146, v147 offset0:2 offset1:3
	s_waitcnt lgkmcnt(0)
	s_barrier
	ds_read_b32 v72, v115 offset:0
	ds_read_b32 v73, v115 offset:260
	ds_read_b32 v74, v115 offset:520
	ds_read_b32 v75, v115 offset:780
	ds_read_b32 v76, v115 offset:1040
	ds_read_b32 v77, v115 offset:1300
	ds_read_b32 v78, v115 offset:1560
	ds_read_b32 v79, v115 offset:1820
	ds_read_b32 v26, v115 offset:128
	ds_read_b32 v27, v115 offset:388
	ds_read_b32 v28, v115 offset:648
	ds_read_b32 v29, v115 offset:908
	ds_read_b32 v30, v115 offset:1168
	ds_read_b32 v31, v115 offset:1428
	ds_read_b32 v32, v115 offset:1688
	ds_read_b32 v33, v115 offset:1948
	s_waitcnt lgkmcnt(8)
	v_cvt_pk_bf16_f32 v124, v72, v73
	v_cvt_pk_bf16_f32 v125, v74, v75
	v_cvt_pk_bf16_f32 v126, v76, v77
	v_cvt_pk_bf16_f32 v127, v78, v79
	global_store_dwordx4 v120, v[124:127], s[0:1]
	s_waitcnt lgkmcnt(0)
	v_cvt_pk_bf16_f32 v128, v26, v27
	v_cvt_pk_bf16_f32 v129, v28, v29
	v_cvt_pk_bf16_f32 v130, v30, v31
	v_cvt_pk_bf16_f32 v131, v32, v33
	global_store_dwordx4 v121, v[128:131], s[0:1]
	s_add_i32 s59, s2, 0x1000
	s_cmp_lt_u32 s59, 0x1000
	s_cbranch_scc0 .Lcv_sd8
	s_lshr_b32 s60, s59, 11
	s_bfe_u32 s71, s59, 0x40007
	s_bfe_u32 s35, s59, 0x30004
	s_and_b32 s51, s59, 15
	s_lshl_b32 s0, s36, 4
	s_add_i32 s71, s71, s0
	s_lshl_b32 s71, s71, 21
	s_lshl_b32 s0, s51, 17
	s_add_i32 s71, s71, s0
	s_lshl_b32 s0, s35, 8
	s_add_i32 s71, s71, s0
	s_cmp_eq_u32 s60, 0
	s_cselect_b32 s88, s52, s54
	s_cselect_b32 s89, s53, s55
	s_add_u32 s88, s88, s71
	s_addc_u32 s89, s89, 0
	s_mov_b32 s94, 11
	s_branch .Lcv_se8

; __device__ __forceinline__ u16 f2bf(float f) { return (u16)(pack2(f, 0.f) & 0xffffu); }
; __device__ __forceinline__ int tid_() { int t = threadIdx.x; asm volatile("" : "+v"(t)); return t; }
; __device__ __forceinline__ void convT_tile(const float* __restrict__ src, int lds, int k0, int c0, u16* __restrict__ dst, int Kd,
;                                            int rbase, int mode, int which, unsigned char* smem, const float* __restrict__ kscale = nullptr) {
;   float* tile = (float*)smem;
;   const int t = tid_();
;   float4 v4[4];
; #pragma unroll
;   for (int i = 0; i < 4; ++i) {
;     const f32x4 w_ = __builtin_nontemporal_load((const f32x4*)(src + (size_t)(k0 + i * 16 + (t >> 4)) * lds + c0 + (t & 15) * 4));
;     v4[i] = make_float4(w_[0], w_[1], w_[2], w_[3]);
;   }
; #pragma unroll
;   for (int i = 0; i < 4; ++i) {
;     const int kk = i * 16 + (t >> 4), cc = (t & 15) * 4;
;     const float sc = kscale ? kscale[k0 + kk] : 1.f;
;     tile[kk * 65 + cc + 0] = v4[i].x * sc; tile[kk * 65 + cc + 1] = v4[i].y * sc;
;     tile[kk * 65 + cc + 2] = v4[i].z * sc; tile[kk * 65 + cc + 3] = v4[i].w * sc;
;   }
;   __syncthreads();
; #pragma unroll
;   for (int i = 0; i < 16; ++i) {
;     const int cc = i * 4 + (t >> 6), kk = t & 63;
;     int row;
;     if (mode == 0) row = rbase + cc;
;     else { const int f = c0 + cc; row = (((f >> 4) * 2 + which) << 4) + (f & 15); }
;     dst[(size_t)row * Kd + k0 + kk] = f2bf(tile[kk * 65 + cc]);
;   }
;   __syncthreads();
; }
; __device__ __forceinline__ void conv_item(const Params& p, int it, unsigned char* smem) {
;     ...
;   if (r < 4096) {
;     const int which = r >> 11, r2 = r & 2047, e = r2 >> 7, r3 = r2 & 127, ct = r3 >> 4, kt = r3 & 15;
;     const float* src = (which ? p.w_up : p.w_gate) + (size_t)(l * 16 + e) * 1024 * 512;
;     convT_tile(src, 512, kt * 64, ct * 64, p.WguT + (size_t)(l * 16 + e) * 1024 * 1024, 1024, 0, 1, which, smem);
;     return;
;   }
;   r -= 4096;
;   {
;     const int e = r >> 7, r3 = r & 127, ct = r3 >> 3, kt = r3 & 7;
;     convT_tile(p.w_down + (size_t)(l * 16 + e) * 512 * 1024, 1024, kt * 64, ct * 64, p.WdT + (size_t)(l * 16 + e) * 1024 * 512, 512, ct * 64, 0, 0, smem);
;   }
.Lcv_se8:
	v_lshl_add_u32 v116, v98, s94, v102
	v_lshl_add_u32 v117, v99, s94, v102
	v_lshl_add_u32 v118, v100, s94, v102
	v_lshl_add_u32 v119, v101, s94, v102
	global_load_dwordx4 v[132:135], v116, s[88:89] nt
	global_load_dwordx4 v[136:139], v117, s[88:89] nt
	global_load_dwordx4 v[140:143], v118, s[88:89] nt
	global_load_dwordx4 v[144:147], v119, s[88:89] nt
	s_add_i32 s59, s2, 0xe00
	s_cmp_lt_u32 s59, 0x1000
	s_cbranch_scc0 .Lcv_dd7
	s_lshr_b32 s60, s59, 11
	s_bfe_u32 s71, s59, 0x40007
	s_bfe_u32 s35, s59, 0x30004
	s_and_b32 s51, s59, 15
	s_lshl_b32 s0, s36, 4
	s_add_i32 s71, s71, s0
	s_lshl_b32 s71, s71, 21
	s_lshl_b32 s35, s35, 7
	s_lshl_b32 s60, s60, 4
	s_add_i32 s35, s35, s60
	s_lshl_b32 s35, s35, 11
	s_add_i32 s71, s71, s35
	s_lshl_b32 s51, s51, 7
	s_add_i32 s71, s71, s51
	s_add_u32 s0, s98, s71
	s_addc_u32 s1, s99, 0
	v_mov_b32_e32 v120, v103
	v_mov_b32_e32 v121, v104
	s_branch .Lcv_de7

; __device__ __forceinline__ u16 f2bf(float f) { return (u16)(pack2(f, 0.f) & 0xffffu); }
; __device__ __forceinline__ int tid_() { int t = threadIdx.x; asm volatile("" : "+v"(t)); return t; }
; __device__ __forceinline__ void convT_tile(const float* __restrict__ src, int lds, int k0, int c0, u16* __restrict__ dst, int Kd,
;                                            int rbase, int mode, int which, unsigned char* smem, const float* __restrict__ kscale = nullptr) {
;   float* tile = (float*)smem;
;   const int t = tid_();
;   float4 v4[4];
; #pragma unroll
;   for (int i = 0; i < 4; ++i) {
;     const f32x4 w_ = __builtin_nontemporal_load((const f32x4*)(src + (size_t)(k0 + i * 16 + (t >> 4)) * lds + c0 + (t & 15) * 4));
;     v4[i] = make_float4(w_[0], w_[1], w_[2], w_[3]);
;   }
; #pragma unroll
;   for (int i = 0; i < 4; ++i) {
;     const int kk = i * 16 + (t >> 4), cc = (t & 15) * 4;
;     const float sc = kscale ? kscale[k0 + kk] : 1.f;
;     tile[kk * 65 + cc + 0] = v4[i].x * sc; tile[kk * 65 + cc + 1] = v4[i].y * sc;
;     tile[kk * 65 + cc + 2] = v4[i].z * sc; tile[kk * 65 + cc + 3] = v4[i].w * sc;
;   }
;   __syncthreads();
; #pragma unroll
;   for (int i = 0; i < 16; ++i) {
;     const int cc = i * 4 + (t >> 6), kk = t & 63;
;     int row;
;     if (mode == 0) row = rbase + cc;
;     else { const int f = c0 + cc; row = (((f >> 4) * 2 + which) << 4) + (f & 15); }
;     dst[(size_t)row * Kd + k0 + kk] = f2bf(tile[kk * 65 + cc]);
;   }
;   __syncthreads();
; }
.Lcv_de7:
	s_waitcnt vmcnt(6)
	ds_write2_b32 v111, v148, v149 offset1:1
	ds_write2_b32 v111, v150, v151 offset0:2 offset1:3
	ds_write2_b32 v112, v152, v153 offset1:1
	ds_write2_b32 v112, v154, v155 offset0:2 offset1:3
	ds_write2_b32 v113, v156, v157 offset1:1
	ds_write2_b32 v113, v158, v159 offset0:2 offset1:3
	ds_write2_b32 v114, v160, v161 offset1:1
	ds_write2_b32 v114, v162, v163 offset0:2 offset1:3
	s_waitcnt lgkmcnt(0)
	s_barrier
	ds_read_b32 v72, v115 offset:16640
	ds_read_b32 v73, v115 offset:16900
	ds_read_b32 v74, v115 offset:17160
	ds_read_b32 v75, v115 offset:17420
	ds_read_b32 v76, v115 offset:17680
	ds_read_b32 v77, v115 offset:17940
	ds_read_b32 v78, v115 offset:18200
	ds_read_b32 v79, v115 offset:18460
	ds_read_b32 v26, v115 offset:16768
	ds_read_b32 v27, v115 offset:17028
	ds_read_b32 v28, v115 offset:17288
	ds_read_b32 v29, v115 offset:17548
	ds_read_b32 v30, v115 offset:17808
	ds_read_b32 v31, v115 offset:18068
	ds_read_b32 v32, v115 offset:18328
	ds_read_b32 v33, v115 offset:18588
	s_waitcnt lgkmcnt(8)
	v_cvt_pk_bf16_f32 v124, v72, v73
	v_cvt_pk_bf16_f32 v125, v74, v75
	v_cvt_pk_bf16_f32 v126, v76, v77
	v_cvt_pk_bf16_f32 v127, v78, v79
	global_store_dwordx4 v120, v[124:127], s[0:1]
	s_waitcnt lgkmcnt(0)
	v_cvt_pk_bf16_f32 v128, v26, v27
	v_cvt_pk_bf16_f32 v129, v28, v29
	v_cvt_pk_bf16_f32 v130, v30, v31
	v_cvt_pk_bf16_f32 v131, v32, v33
	global_store_dwordx4 v121, v[128:131], s[0:1]
	s_add_i32 s59, s2, 0x1200
	s_cmp_lt_u32 s59, 0x1000
	s_cbranch_scc0 .Lcv_sd9
	s_lshr_b32 s60, s59, 11
	s_bfe_u32 s71, s59, 0x40007
	s_bfe_u32 s35, s59, 0x30004
	s_and_b32 s51, s59, 15
	s_lshl_b32 s0, s36, 4
	s_add_i32 s71, s71, s0
	s_lshl_b32 s71, s71, 21
	s_lshl_b32 s0, s51, 17
	s_add_i32 s71, s71, s0
	s_lshl_b32 s0, s35, 8
	s_add_i32 s71, s71, s0
	s_cmp_eq_u32 s60, 0
	s_cselect_b32 s88, s52, s54
	s_cselect_b32 s89, s53, s55
	s_add_u32 s88, s88, s71
	s_addc_u32 s89, s89, 0
	s_mov_b32 s94, 11
	s_branch .Lcv_se9

; __device__ __forceinline__ u16 f2bf(float f) { return (u16)(pack2(f, 0.f) & 0xffffu); }
; __device__ __forceinline__ int tid_() { int t = threadIdx.x; asm volatile("" : "+v"(t)); return t; }
; __device__ __forceinline__ void convT_tile(const float* __restrict__ src, int lds, int k0, int c0, u16* __restrict__ dst, int Kd,
;                                            int rbase, int mode, int which, unsigned char* smem, const float* __restrict__ kscale = nullptr) {
;   float* tile = (float*)smem;
;   const int t = tid_();
;   float4 v4[4];
; #pragma unroll
;   for (int i = 0; i < 4; ++i) {
;     const f32x4 w_ = __builtin_nontemporal_load((const f32x4*)(src + (size_t)(k0 + i * 16 + (t >> 4)) * lds + c0 + (t & 15) * 4));
;     v4[i] = make_float4(w_[0], w_[1], w_[2], w_[3]);
;   }
; #pragma unroll
;   for (int i = 0; i < 4; ++i) {
;     const int kk = i * 16 + (t >> 4), cc = (t & 15) * 4;
;     const float sc = kscale ? kscale[k0 + kk] : 1.f;
;     tile[kk * 65 + cc + 0] = v4[i].x * sc; tile[kk * 65 + cc + 1] = v4[i].y * sc;
;     tile[kk * 65 + cc + 2] = v4[i].z * sc; tile[kk * 65 + cc + 3] = v4[i].w * sc;
;   }
;   __syncthreads();
; #pragma unroll
;   for (int i = 0; i < 16; ++i) {
;     const int cc = i * 4 + (t >> 6), kk = t & 63;
;     int row;
;     if (mode == 0) row = rbase + cc;
;     else { const int f = c0 + cc; row = (((f >> 4) * 2 + which) << 4) + (f & 15); }
;     dst[(size_t)row * Kd + k0 + kk] = f2bf(tile[kk * 65 + cc]);
;   }
;   __syncthreads();
; }
; __device__ __forceinline__ void conv_item(const Params& p, int it, unsigned char* smem) {
;     ...
;   if (r < 4096) {
;     const int which = r >> 11, r2 = r & 2047, e = r2 >> 7, r3 = r2 & 127, ct = r3 >> 4, kt = r3 & 15;
;     const float* src = (which ? p.w_up : p.w_gate) + (size_t)(l * 16 + e) * 1024 * 512;
;     convT_tile(src, 512, kt * 64, ct * 64, p.WguT + (size_t)(l * 16 + e) * 1024 * 1024, 1024, 0, 1, which, smem);
;     return;
;   }
;   r -= 4096;
;   {
;     const int e = r >> 7, r3 = r & 127, ct = r3 >> 3, kt = r3 & 7;
;     convT_tile(p.w_down + (size_t)(l * 16 + e) * 512 * 1024, 1024, kt * 64, ct * 64, p.WdT + (size_t)(l * 16 + e) * 1024 * 512, 512, ct * 64, 0, 0, smem);
;   }
.Lcv_se9:
	v_lshl_add_u32 v116, v98, s94, v102
	v_lshl_add_u32 v117, v99, s94, v102
	v_lshl_add_u32 v118, v100, s94, v102
	v_lshl_add_u32 v119, v101, s94, v102
	global_load_dwordx4 v[148:151], v116, s[88:89] nt
	global_load_dwordx4 v[152:155], v117, s[88:89] nt
	global_load_dwordx4 v[156:159], v118, s[88:89] nt
	global_load_dwordx4 v[160:163], v119, s[88:89] nt
	s_add_i32 s59, s2, 0x1000
	s_cmp_lt_u32 s59, 0x1000
	s_cbranch_scc0 .Lcv_dd8
	s_lshr_b32 s60, s59, 11
	s_bfe_u32 s71, s59, 0x40007
	s_bfe_u32 s35, s59, 0x30004
	s_and_b32 s51, s59, 15
	s_lshl_b32 s0, s36, 4
	s_add_i32 s71, s71, s0
	s_lshl_b32 s71, s71, 21
	s_lshl_b32 s35, s35, 7
	s_lshl_b32 s60, s60, 4
	s_add_i32 s35, s35, s60
	s_lshl_b32 s35, s35, 11
	s_add_i32 s71, s71, s35
	s_lshl_b32 s51, s51, 7
	s_add_i32 s71, s71, s51
	s_add_u32 s0, s98, s71
	s_addc_u32 s1, s99, 0
	v_mov_b32_e32 v120, v103
	v_mov_b32_e32 v121, v104
	s_branch .Lcv_de8

; __device__ __forceinline__ u16 f2bf(float f) { return (u16)(pack2(f, 0.f) & 0xffffu); }
; __device__ __forceinline__ int tid_() { int t = threadIdx.x; asm volatile("" : "+v"(t)); return t; }
; __device__ __forceinline__ void convT_tile(const float* __restrict__ src, int lds, int k0, int c0, u16* __restrict__ dst, int Kd,
;                                            int rbase, int mode, int which, unsigned char* smem, const float* __restrict__ kscale = nullptr) {
;   float* tile = (float*)smem;
;   const int t = tid_();
;   float4 v4[4];
; #pragma unroll
;   for (int i = 0; i < 4; ++i) {
;     const f32x4 w_ = __builtin_nontemporal_load((const f32x4*)(src + (size_t)(k0 + i * 16 + (t >> 4)) * lds + c0 + (t & 15) * 4));
;     v4[i] = make_float4(w_[0], w_[1], w_[2], w_[3]);
;   }
; #pragma unroll
;   for (int i = 0; i < 4; ++i) {
;     const int kk = i * 16 + (t >> 4), cc = (t & 15) * 4;
;     const float sc = kscale ? kscale[k0 + kk] : 1.f;
;     tile[kk * 65 + cc + 0] = v4[i].x * sc; tile[kk * 65 + cc + 1] = v4[i].y * sc;
;     tile[kk * 65 + cc + 2] = v4[i].z * sc; tile[kk * 65 + cc + 3] = v4[i].w * sc;
;   }
;   __syncthreads();
; #pragma unroll
;   for (int i = 0; i < 16; ++i) {
;     const int cc = i * 4 + (t >> 6), kk = t & 63;
;     int row;
;     if (mode == 0) row = rbase + cc;
;     else { const int f = c0 + cc; row = (((f >> 4) * 2 + which) << 4) + (f & 15); }
;     dst[(size_t)row * Kd + k0 + kk] = f2bf(tile[kk * 65 + cc]);
;   }
;   __syncthreads();
; }
.Lcv_de8:
	s_waitcnt vmcnt(6)
	ds_write2_b32 v107, v132, v133 offset1:1
	ds_write2_b32 v107, v134, v135 offset0:2 offset1:3
	ds_write2_b32 v108, v136, v137 offset1:1
	ds_write2_b32 v108, v138, v139 offset0:2 offset1:3
	ds_write2_b32 v109, v140, v141 offset1:1
	ds_write2_b32 v109, v142, v143 offset0:2 offset1:3
	ds_write2_b32 v110, v144, v145 offset1:1
	ds_write2_b32 v110, v146, v147 offset0:2 offset1:3
	s_waitcnt lgkmcnt(0)
	s_barrier
	ds_read_b32 v72, v115 offset:0
	ds_read_b32 v73, v115 offset:260
	ds_read_b32 v74, v115 offset:520
	ds_read_b32 v75, v115 offset:780
	ds_read_b32 v76, v115 offset:1040
	ds_read_b32 v77, v115 offset:1300
	ds_read_b32 v78, v115 offset:1560
	ds_read_b32 v79, v115 offset:1820
	ds_read_b32 v26, v115 offset:128
	ds_read_b32 v27, v115 offset:388
	ds_read_b32 v28, v115 offset:648
	ds_read_b32 v29, v115 offset:908
	ds_read_b32 v30, v115 offset:1168
	ds_read_b32 v31, v115 offset:1428
	ds_read_b32 v32, v115 offset:1688
	ds_read_b32 v33, v115 offset:1948
	s_waitcnt lgkmcnt(8)
	v_cvt_pk_bf16_f32 v124, v72, v73
	v_cvt_pk_bf16_f32 v125, v74, v75
	v_cvt_pk_bf16_f32 v126, v76, v77
	v_cvt_pk_bf16_f32 v127, v78, v79
	global_store_dwordx4 v120, v[124:127], s[0:1]
	s_waitcnt lgkmcnt(0)
	v_cvt_pk_bf16_f32 v128, v26, v27
	v_cvt_pk_bf16_f32 v129, v28, v29
	v_cvt_pk_bf16_f32 v130, v30, v31
	v_cvt_pk_bf16_f32 v131, v32, v33
	global_store_dwordx4 v121, v[128:131], s[0:1]
	s_add_i32 s59, s2, 0x1400
	s_cmp_lt_u32 s59, 0x1000
	s_cbranch_scc0 .Lcv_sd10
	s_lshr_b32 s60, s59, 11
	s_bfe_u32 s71, s59, 0x40007
	s_bfe_u32 s35, s59, 0x30004
	s_and_b32 s51, s59, 15
	s_lshl_b32 s0, s36, 4
	s_add_i32 s71, s71, s0
	s_lshl_b32 s71, s71, 21
	s_lshl_b32 s0, s51, 17
	s_add_i32 s71, s71, s0
	s_lshl_b32 s0, s35, 8
	s_add_i32 s71, s71, s0
	s_cmp_eq_u32 s60, 0
	s_cselect_b32 s88, s52, s54
	s_cselect_b32 s89, s53, s55
	s_add_u32 s88, s88, s71
	s_addc_u32 s89, s89, 0
	s_mov_b32 s94, 11
	s_branch .Lcv_se10

; __device__ __forceinline__ u16 f2bf(float f) { return (u16)(pack2(f, 0.f) & 0xffffu); }
; __device__ __forceinline__ int tid_() { int t = threadIdx.x; asm volatile("" : "+v"(t)); return t; }
; __device__ __forceinline__ void convT_tile(const float* __restrict__ src, int lds, int k0, int c0, u16* __restrict__ dst, int Kd,
;                                            int rbase, int mode, int which, unsigned char* smem, const float* __restrict__ kscale = nullptr) {
;   float* tile = (float*)smem;
;   const int t = tid_();
;   float4 v4[4];
; #pragma unroll
;   for (int i = 0; i < 4; ++i) {
;     const f32x4 w_ = __builtin_nontemporal_load((const f32x4*)(src + (size_t)(k0 + i * 16 + (t >> 4)) * lds + c0 + (t & 15) * 4));
;     v4[i] = make_float4(w_[0], w_[1], w_[2], w_[3]);
;   }
; #pragma unroll
;   for (int i = 0; i < 4; ++i) {
;     const int kk = i * 16 + (t >> 4), cc = (t & 15) * 4;
;     const float sc = kscale ? kscale[k0 + kk] : 1.f;
;     tile[kk * 65 + cc + 0] = v4[i].x * sc; tile[kk * 65 + cc + 1] = v4[i].y * sc;
;     tile[kk * 65 + cc + 2] = v4[i].z * sc; tile[kk * 65 + cc + 3] = v4[i].w * sc;
;   }
;   __syncthreads();
; #pragma unroll
;   for (int i = 0; i < 16; ++i) {
;     const int cc = i * 4 + (t >> 6), kk = t & 63;
;     int row;
;     if (mode == 0) row = rbase + cc;
;     else { const int f = c0 + cc; row = (((f >> 4) * 2 + which) << 4) + (f & 15); }
;     dst[(size_t)row * Kd + k0 + kk] = f2bf(tile[kk * 65 + cc]);
;   }
;   __syncthreads();
; }
; __device__ __forceinline__ void conv_item(const Params& p, int it, unsigned char* smem) {
;     ...
;   if (r < 4096) {
;     const int which = r >> 11, r2 = r & 2047, e = r2 >> 7, r3 = r2 & 127, ct = r3 >> 4, kt = r3 & 15;
;     const float* src = (which ? p.w_up : p.w_gate) + (size_t)(l * 16 + e) * 1024 * 512;
;     convT_tile(src, 512, kt * 64, ct * 64, p.WguT + (size_t)(l * 16 + e) * 1024 * 1024, 1024, 0, 1, which, smem);
;     return;
;   }
;   r -= 4096;
;   {
;     const int e = r >> 7, r3 = r & 127, ct = r3 >> 3, kt = r3 & 7;
;     convT_tile(p.w_down + (size_t)(l * 16 + e) * 512 * 1024, 1024, kt * 64, ct * 64, p.WdT + (size_t)(l * 16 + e) * 1024 * 512, 512, ct * 64, 0, 0, smem);
;   }
.Lcv_se10:
	v_lshl_add_u32 v116, v98, s94, v102
	v_lshl_add_u32 v117, v99, s94, v102
	v_lshl_add_u32 v118, v100, s94, v102
	v_lshl_add_u32 v119, v101, s94, v102
	global_load_dwordx4 v[132:135], v116, s[88:89] nt
	global_load_dwordx4 v[136:139], v117, s[88:89] nt
	global_load_dwordx4 v[140:143], v118, s[88:89] nt
	global_load_dwordx4 v[144:147], v119, s[88:89] nt
	s_add_i32 s59, s2, 0x1200
	s_cmp_lt_u32 s59, 0x1000
	s_cbranch_scc0 .Lcv_dd9
	s_lshr_b32 s60, s59, 11
	s_bfe_u32 s71, s59, 0x40007
	s_bfe_u32 s35, s59, 0x30004
	s_and_b32 s51, s59, 15
	s_lshl_b32 s0, s36, 4
	s_add_i32 s71, s71, s0
	s_lshl_b32 s71, s71, 21
	s_lshl_b32 s35, s35, 7
	s_lshl_b32 s60, s60, 4
	s_add_i32 s35, s35, s60
	s_lshl_b32 s35, s35, 11
	s_add_i32 s71, s71, s35
	s_lshl_b32 s51, s51, 7
	s_add_i32 s71, s71, s51
	s_add_u32 s0, s98, s71
	s_addc_u32 s1, s99, 0
	v_mov_b32_e32 v120, v103
	v_mov_b32_e32 v121, v104
	s_branch .Lcv_de9

; __device__ __forceinline__ u16 f2bf(float f) { return (u16)(pack2(f, 0.f) & 0xffffu); }
; __device__ __forceinline__ int tid_() { int t = threadIdx.x; asm volatile("" : "+v"(t)); return t; }
; __device__ __forceinline__ void convT_tile(const float* __restrict__ src, int lds, int k0, int c0, u16* __restrict__ dst, int Kd,
;                                            int rbase, int mode, int which, unsigned char* smem, const float* __restrict__ kscale = nullptr) {
;   float* tile = (float*)smem;
;   const int t = tid_();
;   float4 v4[4];
; #pragma unroll
;   for (int i = 0; i < 4; ++i) {
;     const f32x4 w_ = __builtin_nontemporal_load((const f32x4*)(src + (size_t)(k0 + i * 16 + (t >> 4)) * lds + c0 + (t & 15) * 4));
;     v4[i] = make_float4(w_[0], w_[1], w_[2], w_[3]);
;   }
; #pragma unroll
;   for (int i = 0; i < 4; ++i) {
;     const int kk = i * 16 + (t >> 4), cc = (t & 15) * 4;
;     const float sc = kscale ? kscale[k0 + kk] : 1.f;
;     tile[kk * 65 + cc + 0] = v4[i].x * sc; tile[kk * 65 + cc + 1] = v4[i].y * sc;
;     tile[kk * 65 + cc + 2] = v4[i].z * sc; tile[kk * 65 + cc + 3] = v4[i].w * sc;
;   }
;   __syncthreads();
; #pragma unroll
;   for (int i = 0; i < 16; ++i) {
;     const int cc = i * 4 + (t >> 6), kk = t & 63;
;     int row;
;     if (mode == 0) row = rbase + cc;
;     else { const int f = c0 + cc; row = (((f >> 4) * 2 + which) << 4) + (f & 15); }
;     dst[(size_t)row * Kd + k0 + kk] = f2bf(tile[kk * 65 + cc]);
;   }
;   __syncthreads();
; }
.Lcv_de9:
	s_waitcnt vmcnt(6)
	ds_write2_b32 v111, v148, v149 offset1:1
	ds_write2_b32 v111, v150, v151 offset0:2 offset1:3
	ds_write2_b32 v112, v152, v153 offset1:1
	ds_write2_b32 v112, v154, v155 offset0:2 offset1:3
	ds_write2_b32 v113, v156, v157 offset1:1
	ds_write2_b32 v113, v158, v159 offset0:2 offset1:3
	ds_write2_b32 v114, v160, v161 offset1:1
	ds_write2_b32 v114, v162, v163 offset0:2 offset1:3
	s_waitcnt lgkmcnt(0)
	s_barrier
	ds_read_b32 v72, v115 offset:16640
	ds_read_b32 v73, v115 offset:16900
	ds_read_b32 v74, v115 offset:17160
	ds_read_b32 v75, v115 offset:17420
	ds_read_b32 v76, v115 offset:17680
	ds_read_b32 v77, v115 offset:17940
	ds_read_b32 v78, v115 offset:18200
	ds_read_b32 v79, v115 offset:18460
	ds_read_b32 v26, v115 offset:16768
	ds_read_b32 v27, v115 offset:17028
	ds_read_b32 v28, v115 offset:17288
	ds_read_b32 v29, v115 offset:17548
	ds_read_b32 v30, v115 offset:17808
	ds_read_b32 v31, v115 offset:18068
	ds_read_b32 v32, v115 offset:18328
	ds_read_b32 v33, v115 offset:18588
	s_waitcnt lgkmcnt(8)
	v_cvt_pk_bf16_f32 v124, v72, v73
	v_cvt_pk_bf16_f32 v125, v74, v75
	v_cvt_pk_bf16_f32 v126, v76, v77
	v_cvt_pk_bf16_f32 v127, v78, v79
	global_store_dwordx4 v120, v[124:127], s[0:1]
	s_waitcnt lgkmcnt(0)
	v_cvt_pk_bf16_f32 v128, v26, v27
	v_cvt_pk_bf16_f32 v129, v28, v29
	v_cvt_pk_bf16_f32 v130, v30, v31
	v_cvt_pk_bf16_f32 v131, v32, v33
	global_store_dwordx4 v121, v[128:131], s[0:1]
	s_add_i32 s59, s2, 0x1600
	s_cmp_lt_u32 s59, 0x1000
	s_cbranch_scc0 .Lcv_sd11
	s_lshr_b32 s60, s59, 11
	s_bfe_u32 s71, s59, 0x40007
	s_bfe_u32 s35, s59, 0x30004
	s_and_b32 s51, s59, 15
	s_lshl_b32 s0, s36, 4
	s_add_i32 s71, s71, s0
	s_lshl_b32 s71, s71, 21
	s_lshl_b32 s0, s51, 17
	s_add_i32 s71, s71, s0
	s_lshl_b32 s0, s35, 8
	s_add_i32 s71, s71, s0
	s_cmp_eq_u32 s60, 0
	s_cselect_b32 s88, s52, s54
	s_cselect_b32 s89, s53, s55
	s_add_u32 s88, s88, s71
	s_addc_u32 s89, s89, 0
	s_mov_b32 s94, 11
	s_branch .Lcv_se11

; __device__ __forceinline__ u16 f2bf(float f) { return (u16)(pack2(f, 0.f) & 0xffffu); }
; __device__ __forceinline__ int tid_() { int t = threadIdx.x; asm volatile("" : "+v"(t)); return t; }
; __device__ __forceinline__ void convT_tile(const float* __restrict__ src, int lds, int k0, int c0, u16* __restrict__ dst, int Kd,
;                                            int rbase, int mode, int which, unsigned char* smem, const float* __restrict__ kscale = nullptr) {
;   float* tile = (float*)smem;
;   const int t = tid_();
;   float4 v4[4];
; #pragma unroll
;   for (int i = 0; i < 4; ++i) {
;     const f32x4 w_ = __builtin_nontemporal_load((const f32x4*)(src + (size_t)(k0 + i * 16 + (t >> 4)) * lds + c0 + (t & 15) * 4));
;     v4[i] = make_float4(w_[0], w_[1], w_[2], w_[3]);
;   }
; #pragma unroll
;   for (int i = 0; i < 4; ++i) {
;     const int kk = i * 16 + (t >> 4), cc = (t & 15) * 4;
;     const float sc = kscale ? kscale[k0 + kk] : 1.f;
;     tile[kk * 65 + cc + 0] = v4[i].x * sc; tile[kk * 65 + cc + 1] = v4[i].y * sc;
;     tile[kk * 65 + cc + 2] = v4[i].z * sc; tile[kk * 65 + cc + 3] = v4[i].w * sc;
;   }
;   __syncthreads();
; #pragma unroll
;   for (int i = 0; i < 16; ++i) {
;     const int cc = i * 4 + (t >> 6), kk = t & 63;
;     int row;
;     if (mode == 0) row = rbase + cc;
;     else { const int f = c0 + cc; row = (((f >> 4) * 2 + which) << 4) + (f & 15); }
;     dst[(size_t)row * Kd + k0 + kk] = f2bf(tile[kk * 65 + cc]);
;   }
;   __syncthreads();
; }
; __device__ __forceinline__ void conv_item(const Params& p, int it, unsigned char* smem) {
;     ...
;   if (r < 4096) {
;     const int which = r >> 11, r2 = r & 2047, e = r2 >> 7, r3 = r2 & 127, ct = r3 >> 4, kt = r3 & 15;
;     const float* src = (which ? p.w_up : p.w_gate) + (size_t)(l * 16 + e) * 1024 * 512;
;     convT_tile(src, 512, kt * 64, ct * 64, p.WguT + (size_t)(l * 16 + e) * 1024 * 1024, 1024, 0, 1, which, smem);
;     return;
;   }
;   r -= 4096;
;   {
;     const int e = r >> 7, r3 = r & 127, ct = r3 >> 3, kt = r3 & 7;
;     convT_tile(p.w_down + (size_t)(l * 16 + e) * 512 * 1024, 1024, kt * 64, ct * 64, p.WdT + (size_t)(l * 16 + e) * 1024 * 512, 512, ct * 64, 0, 0, smem);
;   }
.Lcv_se11:
	v_lshl_add_u32 v116, v98, s94, v102
	v_lshl_add_u32 v117, v99, s94, v102
	v_lshl_add_u32 v118, v100, s94, v102
	v_lshl_add_u32 v119, v101, s94, v102
	global_load_dwordx4 v[148:151], v116, s[88:89] nt
	global_load_dwordx4 v[152:155], v117, s[88:89] nt
	global_load_dwordx4 v[156:159], v118, s[88:89] nt
	global_load_dwordx4 v[160:163], v119, s[88:89] nt
	s_add_i32 s59, s2, 0x1400
	s_cmp_lt_u32 s59, 0x1000
	s_cbranch_scc0 .Lcv_dd10
	s_lshr_b32 s60, s59, 11
	s_bfe_u32 s71, s59, 0x40007
	s_bfe_u32 s35, s59, 0x30004
	s_and_b32 s51, s59, 15
	s_lshl_b32 s0, s36, 4
	s_add_i32 s71, s71, s0
	s_lshl_b32 s71, s71, 21
	s_lshl_b32 s35, s35, 7
	s_lshl_b32 s60, s60, 4
	s_add_i32 s35, s35, s60
	s_lshl_b32 s35, s35, 11
	s_add_i32 s71, s71, s35
	s_lshl_b32 s51, s51, 7
	s_add_i32 s71, s71, s51
	s_add_u32 s0, s98, s71
	s_addc_u32 s1, s99, 0
	v_mov_b32_e32 v120, v103
	v_mov_b32_e32 v121, v104
	s_branch .Lcv_de10

; __device__ __forceinline__ u16 f2bf(float f) { return (u16)(pack2(f, 0.f) & 0xffffu); }
; __device__ __forceinline__ int tid_() { int t = threadIdx.x; asm volatile("" : "+v"(t)); return t; }
; __device__ __forceinline__ void convT_tile(const float* __restrict__ src, int lds, int k0, int c0, u16* __restrict__ dst, int Kd,
;                                            int rbase, int mode, int which, unsigned char* smem, const float* __restrict__ kscale = nullptr) {
;   float* tile = (float*)smem;
;   const int t = tid_();
;   float4 v4[4];
; #pragma unroll
;   for (int i = 0; i < 4; ++i) {
;     const f32x4 w_ = __builtin_nontemporal_load((const f32x4*)(src + (size_t)(k0 + i * 16 + (t >> 4)) * lds + c0 + (t & 15) * 4));
;     v4[i] = make_float4(w_[0], w_[1], w_[2], w_[3]);
;   }
; #pragma unroll
;   for (int i = 0; i < 4; ++i) {
;     const int kk = i * 16 + (t >> 4), cc = (t & 15) * 4;
;     const float sc = kscale ? kscale[k0 + kk] : 1.f;
;     tile[kk * 65 + cc + 0] = v4[i].x * sc; tile[kk * 65 + cc + 1] = v4[i].y * sc;
;     tile[kk * 65 + cc + 2] = v4[i].z * sc; tile[kk * 65 + cc + 3] = v4[i].w * sc;
;   }
;   __syncthreads();
; #pragma unroll
;   for (int i = 0; i < 16; ++i) {
;     const int cc = i * 4 + (t >> 6), kk = t & 63;
;     int row;
;     if (mode == 0) row = rbase + cc;
;     else { const int f = c0 + cc; row = (((f >> 4) * 2 + which) << 4) + (f & 15); }
;     dst[(size_t)row * Kd + k0 + kk] = f2bf(tile[kk * 65 + cc]);
;   }
;   __syncthreads();
; }
.Lcv_de10:
	s_waitcnt vmcnt(6)
	ds_write2_b32 v107, v132, v133 offset1:1
	ds_write2_b32 v107, v134, v135 offset0:2 offset1:3
	ds_write2_b32 v108, v136, v137 offset1:1
	ds_write2_b32 v108, v138, v139 offset0:2 offset1:3
	ds_write2_b32 v109, v140, v141 offset1:1
	ds_write2_b32 v109, v142, v143 offset0:2 offset1:3
	ds_write2_b32 v110, v144, v145 offset1:1
	ds_write2_b32 v110, v146, v147 offset0:2 offset1:3
	s_waitcnt lgkmcnt(0)
	s_barrier
	ds_read_b32 v72, v115 offset:0
	ds_read_b32 v73, v115 offset:260
	ds_read_b32 v74, v115 offset:520
	ds_read_b32 v75, v115 offset:780
	ds_read_b32 v76, v115 offset:1040
	ds_read_b32 v77, v115 offset:1300
	ds_read_b32 v78, v115 offset:1560
	ds_read_b32 v79, v115 offset:1820
	ds_read_b32 v26, v115 offset:128
	ds_read_b32 v27, v115 offset:388
	ds_read_b32 v28, v115 offset:648
	ds_read_b32 v29, v115 offset:908
	ds_read_b32 v30, v115 offset:1168
	ds_read_b32 v31, v115 offset:1428
	ds_read_b32 v32, v115 offset:1688
	ds_read_b32 v33, v115 offset:1948
	s_waitcnt lgkmcnt(8)
	v_cvt_pk_bf16_f32 v124, v72, v73
	v_cvt_pk_bf16_f32 v125, v74, v75
	v_cvt_pk_bf16_f32 v126, v76, v77
	v_cvt_pk_bf16_f32 v127, v78, v79
	global_store_dwordx4 v120, v[124:127], s[0:1]
	s_waitcnt lgkmcnt(0)
	v_cvt_pk_bf16_f32 v128, v26, v27
	v_cvt_pk_bf16_f32 v129, v28, v29
	v_cvt_pk_bf16_f32 v130, v30, v31
	v_cvt_pk_bf16_f32 v131, v32, v33
	global_store_dwordx4 v121, v[128:131], s[0:1]
	s_add_i32 s59, s2, 0x1600
	s_cmp_lt_u32 s59, 0x1000
	s_cbranch_scc0 .Lcv_dd11
	s_lshr_b32 s60, s59, 11
	s_bfe_u32 s71, s59, 0x40007
	s_bfe_u32 s35, s59, 0x30004
	s_and_b32 s51, s59, 15
	s_lshl_b32 s0, s36, 4
	s_add_i32 s71, s71, s0
	s_lshl_b32 s71, s71, 21
	s_lshl_b32 s35, s35, 7
	s_lshl_b32 s60, s60, 4
	s_add_i32 s35, s35, s60
	s_lshl_b32 s35, s35, 11
	s_add_i32 s71, s71, s35
	s_lshl_b32 s51, s51, 7
	s_add_i32 s71, s71, s51
	s_add_u32 s0, s98, s71
	s_addc_u32 s1, s99, 0
	v_mov_b32_e32 v120, v103
	v_mov_b32_e32 v121, v104
	s_branch .Lcv_de11

; __device__ __forceinline__ u16 f2bf(float f) { return (u16)(pack2(f, 0.f) & 0xffffu); }
; __device__ __forceinline__ void convT_tile(const float* __restrict__ src, int lds, int k0, int c0, u16* __restrict__ dst, int Kd,
;                                            int rbase, int mode, int which, unsigned char* smem, const float* __restrict__ kscale = nullptr) {
;     ...
;     const f32x4 w_ = __builtin_nontemporal_load((const f32x4*)(src + (size_t)(k0 + i * 16 + (t >> 4)) * lds + c0 + (t & 15) * 4));
;     v4[i] = make_float4(w_[0], w_[1], w_[2], w_[3]);
;   }
; #pragma unroll
;   for (int i = 0; i < 4; ++i) {
;     const int kk = i * 16 + (t >> 4), cc = (t & 15) * 4;
;     const float sc = kscale ? kscale[k0 + kk] : 1.f;
;     tile[kk * 65 + cc + 0] = v4[i].x * sc; tile[kk * 65 + cc + 1] = v4[i].y * sc;
;     tile[kk * 65 + cc + 2] = v4[i].z * sc; tile[kk * 65 + cc + 3] = v4[i].w * sc;
;   }
;   __syncthreads();
; #pragma unroll
;   for (int i = 0; i < 16; ++i) {
;     const int cc = i * 4 + (t >> 6), kk = t & 63;
;     int row;
;     if (mode == 0) row = rbase + cc;
;     else { const int f = c0 + cc; row = (((f >> 4) * 2 + which) << 4) + (f & 15); }
;     dst[(size_t)row * Kd + k0 + kk] = f2bf(tile[kk * 65 + cc]);
;   }
;   __syncthreads();
; __device__ __forceinline__ void phase_attn(const Params& p, int l, bool last, unsigned char* smem) {
;     ...
;   for (int q = j; q < 64; q += gb) attn_item(p, x >> 2, x & 3, 2 + q, shift, smem);
;   if (!last)
;     for (int q = j; q < 2; q += gb) attn_item(p, x >> 2, x & 3, q, shift, smem);
.Lcv_de11:
	s_waitcnt vmcnt(2)
	ds_write2_b32 v111, v148, v149 offset1:1
	ds_write2_b32 v111, v150, v151 offset0:2 offset1:3
	ds_write2_b32 v112, v152, v153 offset1:1
	ds_write2_b32 v112, v154, v155 offset0:2 offset1:3
	ds_write2_b32 v113, v156, v157 offset1:1
	ds_write2_b32 v113, v158, v159 offset0:2 offset1:3
	ds_write2_b32 v114, v160, v161 offset1:1
	ds_write2_b32 v114, v162, v163 offset0:2 offset1:3
	s_waitcnt lgkmcnt(0)
	s_barrier
	ds_read_b32 v72, v115 offset:16640
	ds_read_b32 v73, v115 offset:16900
	ds_read_b32 v74, v115 offset:17160
	ds_read_b32 v75, v115 offset:17420
	ds_read_b32 v76, v115 offset:17680
	ds_read_b32 v77, v115 offset:17940
	ds_read_b32 v78, v115 offset:18200
	ds_read_b32 v79, v115 offset:18460
	ds_read_b32 v26, v115 offset:16768
	ds_read_b32 v27, v115 offset:17028
	ds_read_b32 v28, v115 offset:17288
	ds_read_b32 v29, v115 offset:17548
	ds_read_b32 v30, v115 offset:17808
	ds_read_b32 v31, v115 offset:18068
	ds_read_b32 v32, v115 offset:18328
	ds_read_b32 v33, v115 offset:18588
	s_waitcnt lgkmcnt(8)
	v_cvt_pk_bf16_f32 v124, v72, v73
	v_cvt_pk_bf16_f32 v125, v74, v75
	v_cvt_pk_bf16_f32 v126, v76, v77
	v_cvt_pk_bf16_f32 v127, v78, v79
	global_store_dwordx4 v120, v[124:127], s[0:1]
	s_waitcnt lgkmcnt(0)
	v_cvt_pk_bf16_f32 v128, v26, v27
	v_cvt_pk_bf16_f32 v129, v28, v29
	v_cvt_pk_bf16_f32 v130, v30, v31
	v_cvt_pk_bf16_f32 v131, v32, v33
	global_store_dwordx4 v121, v[128:131], s[0:1]
	s_waitcnt vmcnt(0) lgkmcnt(0)
	s_barrier
	s_cmp_eq_u32 s32, 0
	s_cbranch_scc1 .Lcv_ret_pre
	s_branch .Lcv_ret_post
.LBB0_776:
	s_bitcmp1_b32 s2, 8
	s_cbranch_scc1 .Lcv_ret_post
	s_mov_b32 s32, 1
	s_branch .Lcv_entry
